# GEMM MFMA phases: each B fragment shared by four consecutive MFMAs (both row halves), A never repeated back-to-back
# speedup vs baseline: 1.0045x; 1.0045x over previous
; #define PG8_STAGE(bufoff, gbase, voff) do { _Pragma("unroll") for (int _i = 0; _i < 2; ++_i) \
;         __builtin_amdgcn_global_load_lds((const unsigned*)((const char*)(gbase) + (voff)[_i]), (LAS unsigned*)(lds + (bufoff) + ldsw + _i * 8192), 16, 0, 0); } while (0)
; #define PG8_LDA(dst, b, h) do { _Pragma("unroll") for (int m = 0; m < 4; ++m) _Pragma("unroll") for (int k = 0; k < 2; ++k) dst[m][k] = *(const LAS bf16x8*)(lds + PG8_SA(b, h) + aoff + m * 2048 + k * 1024); } while (0)
; #define PG8_LDB(dst, b, h) do { _Pragma("unroll") for (int n = 0; n < 2; ++n) _Pragma("unroll") for (int k = 0; k < 2; ++k) dst[n][k] = *(const LAS bf16x8*)(lds + PG8_SB(b, h) + boff + n * 2048 + k * 1024); } while (0)
; #define PG8_MMA(ai, bj, At, Bt) do { __builtin_amdgcn_s_setprio(1); _Pragma("unroll") for (int m = 0; m < 4; ++m) _Pragma("unroll") for (int n = 0; n < 2; ++n) _Pragma("unroll") for (int k = 0; k < 2; ++k) \
;         acc[ai][bj][m][n] = __builtin_amdgcn_mfma_f32_16x16x32_bf16(Bt[n][k], At[m][k], acc[ai][bj][m][n], 0, 0, 0); __builtin_amdgcn_s_setprio(0); } while (0)
; #define PG8_WAIT_V(n) asm volatile("s_waitcnt vmcnt(" #n ")" ::: "memory")
; #define PG8_WAIT_L(n) asm volatile("s_waitcnt lgkmcnt(" #n ")" ::: "memory")
; #define PG8_BAR __builtin_amdgcn_s_barrier()
; #define PG8_SCHED __builtin_amdgcn_sched_barrier(0)
; template <class Epi>
; __device__ __forceinline__ void gemm_phase(LAS unsigned char* lds, const Gemm g, const StaticOrder& S, const Epi& E) {
;     ...
;         for (int t = 0; t < nt; t += 2) {
;             const bool last = (t == nt - 2);
;             const char* a1 = cA + (size_t)(t + 1) * kstep;
;             const char* a2 = last ? nA : cA + (size_t)(t + 2) * kstep; const char* b2 = last ? nB : cB + (size_t)(t + 2) * kstep;
;             const char* a3 = a2 + kstep; const char* b3 = b2 + kstep;
;             PG8_LDB(B0, 0, 0); PG8_LDB(B1, 0, 1); PG8_SCHED; PG8_LDA(At, 0, 0); PG8_STAGE(PG8_SA(1, 1), a1 + hA, voffA);
;             PG8_WAIT_V(8); PG8_WAIT_L(0); PG8_BAR; PG8_MMA(0, 0, At, B0); PG8_MMA(0, 1, At, B1); PG8_BAR; PG8_SCHED;
;             PG8_LDA(At, 0, 1); PG8_STAGE(PG8_SB(0, 0), b2, voffB); PG8_STAGE(PG8_SB(0, 1), b2 + hB, voffB); PG8_STAGE(PG8_SA(0, 0), a2, voffA);
;             PG8_WAIT_V(8); PG8_WAIT_L(0); PG8_BAR; PG8_MMA(1, 0, At, B0); PG8_MMA(1, 1, At, B1); PG8_BAR; PG8_SCHED;
.LBB0_132:
	s_add_u32 s34, s8, 0xfffc0080
	s_addc_u32 s35, s9, -1
	s_add_i32 s42, 0, 0x10000
	s_cmp_eq_u32 s41, 12
	s_cselect_b32 s37, s7, s35
	s_cselect_b32 s36, s27, s34
	v_add_u32_e32 v153, s42, v139
	s_cselect_b32 s35, s25, s40
	s_cselect_b32 s34, s38, s39
	s_add_i32 s44, 0, 0x14000
	ds_read_b128 v[166:169], v153
	ds_read_b128 v[170:173], v153 offset:1024
	ds_read_b128 v[174:177], v153 offset:2048
	ds_read_b128 v[182:185], v153 offset:3072
	v_add_u32_e32 v153, s44, v139
	ds_read_b128 v[186:189], v153
	ds_read_b128 v[190:193], v153 offset:1024
	ds_read_b128 v[194:197], v153 offset:2048
	ds_read_b128 v[198:201], v153 offset:3072
	v_lshl_add_u64 v[178:179], s[8:9], 0, v[162:163]
	s_add_i32 m0, s19, 0xc000
	ds_read_b128 v[202:205], v149
	ds_read_b128 v[206:209], v149 offset:1024
	ds_read_b128 v[210:213], v149 offset:2048
	ds_read_b128 v[214:217], v149 offset:3072
	ds_read_b128 v[218:221], v149 offset:4096
	ds_read_b128 v[232:235], v149 offset:5120
	ds_read_b128 v[236:239], v149 offset:6144
	ds_read_b128 v[240:243], v149 offset:7168
	global_load_lds_dwordx4 v[178:179], off
	v_lshl_add_u64 v[178:179], s[8:9], 0, v[164:165]
	s_add_i32 m0, s19, 0xe000
	s_nop 0
	global_load_lds_dwordx4 v[178:179], off
	s_waitcnt vmcnt(8)
	s_waitcnt lgkmcnt(0)
	s_barrier
	s_setprio 1
	v_mfma_f32_16x16x32_bf16 v[126:129], v[166:169], v[202:205], v[126:129]
	v_mfma_f32_16x16x32_bf16 v[122:125], v[174:177], v[202:205], v[122:125]
	v_mfma_f32_16x16x32_bf16 v[118:121], v[186:189], v[202:205], v[118:121]
	v_mfma_f32_16x16x32_bf16 v[114:117], v[194:197], v[202:205], v[114:117]
	v_mfma_f32_16x16x32_bf16 v[110:113], v[166:169], v[210:213], v[110:113]
	v_mfma_f32_16x16x32_bf16 v[106:109], v[174:177], v[210:213], v[106:109]
	v_mfma_f32_16x16x32_bf16 v[102:105], v[186:189], v[210:213], v[102:105]
	v_mfma_f32_16x16x32_bf16 v[98:101], v[194:197], v[210:213], v[98:101]
	v_mfma_f32_16x16x32_bf16 v[94:97], v[166:169], v[218:221], v[94:97]
	v_mfma_f32_16x16x32_bf16 v[90:93], v[174:177], v[218:221], v[90:93]
	v_mfma_f32_16x16x32_bf16 v[86:89], v[186:189], v[218:221], v[86:89]
	v_mfma_f32_16x16x32_bf16 v[82:85], v[194:197], v[218:221], v[82:85]
	v_mfma_f32_16x16x32_bf16 v[78:81], v[166:169], v[236:239], v[78:81]
	v_mfma_f32_16x16x32_bf16 v[74:77], v[174:177], v[236:239], v[74:77]
	v_mfma_f32_16x16x32_bf16 v[70:73], v[186:189], v[236:239], v[70:73]
	v_mfma_f32_16x16x32_bf16 v[66:69], v[194:197], v[236:239], v[66:69]
	v_mfma_f32_16x16x32_bf16 v[126:129], v[170:173], v[206:209], v[126:129]
	v_mfma_f32_16x16x32_bf16 v[122:125], v[182:185], v[206:209], v[122:125]
	v_mfma_f32_16x16x32_bf16 v[118:121], v[190:193], v[206:209], v[118:121]
	v_mfma_f32_16x16x32_bf16 v[114:117], v[198:201], v[206:209], v[114:117]
	v_mfma_f32_16x16x32_bf16 v[110:113], v[170:173], v[214:217], v[110:113]
	v_mfma_f32_16x16x32_bf16 v[106:109], v[182:185], v[214:217], v[106:109]
	v_mfma_f32_16x16x32_bf16 v[102:105], v[190:193], v[214:217], v[102:105]
	v_mfma_f32_16x16x32_bf16 v[98:101], v[198:201], v[214:217], v[98:101]
	v_mfma_f32_16x16x32_bf16 v[94:97], v[170:173], v[232:235], v[94:97]
	v_mfma_f32_16x16x32_bf16 v[90:93], v[182:185], v[232:235], v[90:93]
	v_mfma_f32_16x16x32_bf16 v[86:89], v[190:193], v[232:235], v[86:89]
	v_mfma_f32_16x16x32_bf16 v[82:85], v[198:201], v[232:235], v[82:85]
	v_mfma_f32_16x16x32_bf16 v[78:81], v[170:173], v[240:243], v[78:81]
	v_mfma_f32_16x16x32_bf16 v[74:77], v[182:185], v[240:243], v[74:77]
	v_mfma_f32_16x16x32_bf16 v[70:73], v[190:193], v[240:243], v[70:73]
	v_mfma_f32_16x16x32_bf16 v[66:69], v[198:201], v[240:243], v[66:69]
	s_setprio 0
	s_barrier
	s_add_i32 s42, s42, s51
	v_lshl_add_u64 v[178:179], s[34:35], 0, v[132:133]
	s_mov_b32 m0, s42
	ds_read_b128 v[202:205], v149 offset:16384
	ds_read_b128 v[206:209], v149 offset:17408
	ds_read_b128 v[210:213], v149 offset:18432
	ds_read_b128 v[214:217], v149 offset:19456
	ds_read_b128 v[218:221], v149 offset:20480
	ds_read_b128 v[232:235], v149 offset:21504
	ds_read_b128 v[236:239], v149 offset:22528
	ds_read_b128 v[240:243], v149 offset:23552
	global_load_lds_dwordx4 v[178:179], off
	s_add_i32 m0, s42, 0x2000
	s_add_u32 s42, s34, 0x40000
	v_lshl_add_u64 v[244:245], s[34:35], 0, v[136:137]
	s_addc_u32 s43, s35, 0
	s_add_i32 s44, s44, s51
	global_load_lds_dwordx4 v[244:245], off
	v_lshl_add_u64 v[246:247], s[42:43], 0, v[132:133]
	s_mov_b32 m0, s44
	v_lshl_add_u64 v[248:249], s[36:37], 0, v[134:135]
	global_load_lds_dwordx4 v[246:247], off
	v_lshl_add_u64 v[246:247], s[42:43], 0, v[136:137]
	s_add_i32 m0, s44, 0x2000
	s_nop 0
	global_load_lds_dwordx4 v[246:247], off
	v_lshl_add_u64 v[246:247], s[36:37], 0, v[130:131]
	s_mov_b32 m0, s19
	s_nop 0
	global_load_lds_dwordx4 v[246:247], off
	s_mov_b32 m0, s56
	s_nop 0
	global_load_lds_dwordx4 v[248:249], off
	s_waitcnt vmcnt(8)
	s_waitcnt lgkmcnt(0)
	s_barrier
; #define PG8_STAGE(bufoff, gbase, voff) do { _Pragma("unroll") for (int _i = 0; _i < 2; ++_i) \
;         __builtin_amdgcn_global_load_lds((const unsigned*)((const char*)(gbase) + (voff)[_i]), (LAS unsigned*)(lds + (bufoff) + ldsw + _i * 8192), 16, 0, 0); } while (0)
; #define PG8_LDA(dst, b, h) do { _Pragma("unroll") for (int m = 0; m < 4; ++m) _Pragma("unroll") for (int k = 0; k < 2; ++k) dst[m][k] = *(const LAS bf16x8*)(lds + PG8_SA(b, h) + aoff + m * 2048 + k * 1024); } while (0)
; #define PG8_LDB(dst, b, h) do { _Pragma("unroll") for (int n = 0; n < 2; ++n) _Pragma("unroll") for (int k = 0; k < 2; ++k) dst[n][k] = *(const LAS bf16x8*)(lds + PG8_SB(b, h) + boff + n * 2048 + k * 1024); } while (0)
; #define PG8_MMA(ai, bj, At, Bt) do { __builtin_amdgcn_s_setprio(1); _Pragma("unroll") for (int m = 0; m < 4; ++m) _Pragma("unroll") for (int n = 0; n < 2; ++n) _Pragma("unroll") for (int k = 0; k < 2; ++k) \
;         acc[ai][bj][m][n] = __builtin_amdgcn_mfma_f32_16x16x32_bf16(Bt[n][k], At[m][k], acc[ai][bj][m][n], 0, 0, 0); __builtin_amdgcn_s_setprio(0); } while (0)
; #define PG8_WAIT_V(n) asm volatile("s_waitcnt vmcnt(" #n ")" ::: "memory")
; #define PG8_WAIT_L(n) asm volatile("s_waitcnt lgkmcnt(" #n ")" ::: "memory")
; #define PG8_BAR __builtin_amdgcn_s_barrier()
; #define PG8_SCHED __builtin_amdgcn_sched_barrier(0)
; template <class Epi>
; __device__ __forceinline__ void gemm_phase(LAS unsigned char* lds, const Gemm g, const StaticOrder& S, const Epi& E) {
;     ...
;             PG8_WAIT_V(8); PG8_WAIT_L(0); PG8_BAR; PG8_MMA(1, 0, At, B0); PG8_MMA(1, 1, At, B1); PG8_BAR; PG8_SCHED;
;             PG8_LDB(B0, 1, 0); PG8_LDB(B1, 1, 1); PG8_SCHED; PG8_LDA(At, 1, 0); PG8_STAGE(PG8_SA(0, 1), a2 + hA, voffA);
;             PG8_WAIT_V(8); PG8_WAIT_L(0); PG8_BAR; PG8_MMA(0, 0, At, B0); PG8_MMA(0, 1, At, B1); PG8_BAR; PG8_SCHED;
	s_setprio 1
	v_mfma_f32_16x16x32_bf16 v[62:65], v[166:169], v[202:205], v[62:65]
	v_mfma_f32_16x16x32_bf16 v[58:61], v[174:177], v[202:205], v[58:61]
	v_mfma_f32_16x16x32_bf16 v[54:57], v[186:189], v[202:205], v[54:57]
	v_mfma_f32_16x16x32_bf16 v[50:53], v[194:197], v[202:205], v[50:53]
	v_mfma_f32_16x16x32_bf16 v[46:49], v[166:169], v[210:213], v[46:49]
	v_mfma_f32_16x16x32_bf16 v[42:45], v[174:177], v[210:213], v[42:45]
	v_mfma_f32_16x16x32_bf16 v[38:41], v[186:189], v[210:213], v[38:41]
	v_mfma_f32_16x16x32_bf16 v[34:37], v[194:197], v[210:213], v[34:37]
	v_mfma_f32_16x16x32_bf16 v[30:33], v[166:169], v[218:221], v[30:33]
	v_mfma_f32_16x16x32_bf16 v[26:29], v[174:177], v[218:221], v[26:29]
	v_mfma_f32_16x16x32_bf16 v[22:25], v[186:189], v[218:221], v[22:25]
	v_mfma_f32_16x16x32_bf16 v[18:21], v[194:197], v[218:221], v[18:21]
	v_mfma_f32_16x16x32_bf16 v[14:17], v[166:169], v[236:239], v[14:17]
	v_mfma_f32_16x16x32_bf16 v[10:13], v[174:177], v[236:239], v[10:13]
	v_mfma_f32_16x16x32_bf16 v[6:9], v[186:189], v[236:239], v[6:9]
	v_mfma_f32_16x16x32_bf16 v[2:5], v[194:197], v[236:239], v[2:5]
	v_mfma_f32_16x16x32_bf16 v[62:65], v[170:173], v[206:209], v[62:65]
	v_mfma_f32_16x16x32_bf16 v[58:61], v[182:185], v[206:209], v[58:61]
	v_mfma_f32_16x16x32_bf16 v[54:57], v[190:193], v[206:209], v[54:57]
	v_mfma_f32_16x16x32_bf16 v[50:53], v[198:201], v[206:209], v[50:53]
	v_mfma_f32_16x16x32_bf16 v[46:49], v[170:173], v[214:217], v[46:49]
	v_mfma_f32_16x16x32_bf16 v[42:45], v[182:185], v[214:217], v[42:45]
	v_mfma_f32_16x16x32_bf16 v[38:41], v[190:193], v[214:217], v[38:41]
	v_mfma_f32_16x16x32_bf16 v[34:37], v[198:201], v[214:217], v[34:37]
	v_mfma_f32_16x16x32_bf16 v[30:33], v[170:173], v[232:235], v[30:33]
	v_mfma_f32_16x16x32_bf16 v[26:29], v[182:185], v[232:235], v[26:29]
	v_mfma_f32_16x16x32_bf16 v[22:25], v[190:193], v[232:235], v[22:25]
	v_mfma_f32_16x16x32_bf16 v[18:21], v[198:201], v[232:235], v[18:21]
	v_mfma_f32_16x16x32_bf16 v[14:17], v[170:173], v[240:243], v[14:17]
	v_mfma_f32_16x16x32_bf16 v[10:13], v[182:185], v[240:243], v[10:13]
	v_mfma_f32_16x16x32_bf16 v[6:9], v[190:193], v[240:243], v[6:9]
	v_mfma_f32_16x16x32_bf16 v[2:5], v[198:201], v[240:243], v[2:5]
	s_setprio 0
	s_barrier
	s_add_i32 s42, 0, 0x18000
	v_add_u32_e32 v153, s42, v139
	s_add_i32 s43, 0, 0x1c000
	ds_read_b128 v[166:169], v153
	ds_read_b128 v[170:173], v153 offset:1024
	ds_read_b128 v[174:177], v153 offset:2048
	ds_read_b128 v[182:185], v153 offset:3072
	v_add_u32_e32 v153, s43, v139
	ds_read_b128 v[186:189], v153
	ds_read_b128 v[190:193], v153 offset:1024
	ds_read_b128 v[194:197], v153 offset:2048
	ds_read_b128 v[198:201], v153 offset:3072
	s_add_u32 s36, s36, 0x40000
	s_addc_u32 s37, s37, 0
	s_mov_b32 m0, s57
	v_lshl_add_u64 v[250:251], s[36:37], 0, v[130:131]
	ds_read_b128 v[202:205], v149 offset:32768
	ds_read_b128 v[206:209], v149 offset:33792
	ds_read_b128 v[210:213], v149 offset:34816
	ds_read_b128 v[214:217], v149 offset:35840
	ds_read_b128 v[218:221], v149 offset:36864
	ds_read_b128 v[232:235], v149 offset:37888
	ds_read_b128 v[236:239], v149 offset:38912
	ds_read_b128 v[240:243], v149 offset:39936
	global_load_lds_dwordx4 v[250:251], off
	v_lshl_add_u64 v[250:251], s[36:37], 0, v[134:135]
	s_mov_b32 m0, s58
	s_nop 0
	global_load_lds_dwordx4 v[250:251], off
	s_waitcnt vmcnt(8)
	s_waitcnt lgkmcnt(0)
	s_barrier
	s_setprio 1
	v_mfma_f32_16x16x32_bf16 v[126:129], v[166:169], v[202:205], v[126:129]
	v_mfma_f32_16x16x32_bf16 v[122:125], v[174:177], v[202:205], v[122:125]
	v_mfma_f32_16x16x32_bf16 v[118:121], v[186:189], v[202:205], v[118:121]
	v_mfma_f32_16x16x32_bf16 v[114:117], v[194:197], v[202:205], v[114:117]
	v_mfma_f32_16x16x32_bf16 v[110:113], v[166:169], v[210:213], v[110:113]
	v_mfma_f32_16x16x32_bf16 v[106:109], v[174:177], v[210:213], v[106:109]
	v_mfma_f32_16x16x32_bf16 v[102:105], v[186:189], v[210:213], v[102:105]
	v_mfma_f32_16x16x32_bf16 v[98:101], v[194:197], v[210:213], v[98:101]
	v_mfma_f32_16x16x32_bf16 v[94:97], v[166:169], v[218:221], v[94:97]
	v_mfma_f32_16x16x32_bf16 v[90:93], v[174:177], v[218:221], v[90:93]
	v_mfma_f32_16x16x32_bf16 v[86:89], v[186:189], v[218:221], v[86:89]
	v_mfma_f32_16x16x32_bf16 v[82:85], v[194:197], v[218:221], v[82:85]
	v_mfma_f32_16x16x32_bf16 v[78:81], v[166:169], v[236:239], v[78:81]
	v_mfma_f32_16x16x32_bf16 v[74:77], v[174:177], v[236:239], v[74:77]
	v_mfma_f32_16x16x32_bf16 v[70:73], v[186:189], v[236:239], v[70:73]
	v_mfma_f32_16x16x32_bf16 v[66:69], v[194:197], v[236:239], v[66:69]
	v_mfma_f32_16x16x32_bf16 v[126:129], v[170:173], v[206:209], v[126:129]
	v_mfma_f32_16x16x32_bf16 v[122:125], v[182:185], v[206:209], v[122:125]
	v_mfma_f32_16x16x32_bf16 v[118:121], v[190:193], v[206:209], v[118:121]
	v_mfma_f32_16x16x32_bf16 v[114:117], v[198:201], v[206:209], v[114:117]
	v_mfma_f32_16x16x32_bf16 v[110:113], v[170:173], v[214:217], v[110:113]
	v_mfma_f32_16x16x32_bf16 v[106:109], v[182:185], v[214:217], v[106:109]
	v_mfma_f32_16x16x32_bf16 v[102:105], v[190:193], v[214:217], v[102:105]
	v_mfma_f32_16x16x32_bf16 v[98:101], v[198:201], v[214:217], v[98:101]
	v_mfma_f32_16x16x32_bf16 v[94:97], v[170:173], v[232:235], v[94:97]
	v_mfma_f32_16x16x32_bf16 v[90:93], v[182:185], v[232:235], v[90:93]
	v_mfma_f32_16x16x32_bf16 v[86:89], v[190:193], v[232:235], v[86:89]
	v_mfma_f32_16x16x32_bf16 v[82:85], v[198:201], v[232:235], v[82:85]
	v_mfma_f32_16x16x32_bf16 v[78:81], v[170:173], v[240:243], v[78:81]
	v_mfma_f32_16x16x32_bf16 v[74:77], v[182:185], v[240:243], v[74:77]
	v_mfma_f32_16x16x32_bf16 v[70:73], v[190:193], v[240:243], v[70:73]
	v_mfma_f32_16x16x32_bf16 v[66:69], v[198:201], v[240:243], v[66:69]
	s_setprio 0
	s_barrier
; #define PG8_STAGE(bufoff, gbase, voff) do { _Pragma("unroll") for (int _i = 0; _i < 2; ++_i) \
;         __builtin_amdgcn_global_load_lds((const unsigned*)((const char*)(gbase) + (voff)[_i]), (LAS unsigned*)(lds + (bufoff) + ldsw + _i * 8192), 16, 0, 0); } while (0)
; #define PG8_LDA(dst, b, h) do { _Pragma("unroll") for (int m = 0; m < 4; ++m) _Pragma("unroll") for (int k = 0; k < 2; ++k) dst[m][k] = *(const LAS bf16x8*)(lds + PG8_SA(b, h) + aoff + m * 2048 + k * 1024); } while (0)
; #define PG8_MMA(ai, bj, At, Bt) do { __builtin_amdgcn_s_setprio(1); _Pragma("unroll") for (int m = 0; m < 4; ++m) _Pragma("unroll") for (int n = 0; n < 2; ++n) _Pragma("unroll") for (int k = 0; k < 2; ++k) \
;         acc[ai][bj][m][n] = __builtin_amdgcn_mfma_f32_16x16x32_bf16(Bt[n][k], At[m][k], acc[ai][bj][m][n], 0, 0, 0); __builtin_amdgcn_s_setprio(0); } while (0)
; #define PG8_WAIT_V(n) asm volatile("s_waitcnt vmcnt(" #n ")" ::: "memory")
; #define PG8_WAIT_L(n) asm volatile("s_waitcnt lgkmcnt(" #n ")" ::: "memory")
; #define PG8_BAR __builtin_amdgcn_s_barrier()
; #define PG8_SCHED __builtin_amdgcn_sched_barrier(0)
; template <class Epi>
; __device__ __forceinline__ void gemm_phase(LAS unsigned char* lds, const Gemm g, const StaticOrder& S, const Epi& E) {
;     ...
;             PG8_LDA(At, 1, 1); PG8_STAGE(PG8_SB(1, 0), b3, voffB); PG8_STAGE(PG8_SB(1, 1), b3 + hB, voffB); PG8_STAGE(PG8_SA(1, 0), a3, voffA);
;             PG8_WAIT_V(8); PG8_WAIT_L(0); PG8_BAR; PG8_MMA(1, 0, At, B0); PG8_MMA(1, 1, At, B1); PG8_BAR; PG8_SCHED;
;         }
	s_add_i32 s36, s42, s51
	v_lshl_add_u64 v[178:179], v[178:179], 0, s[88:89]
	s_mov_b32 m0, s36
	ds_read_b128 v[202:205], v149 offset:49152
	ds_read_b128 v[206:209], v149 offset:50176
	ds_read_b128 v[210:213], v149 offset:51200
	ds_read_b128 v[214:217], v149 offset:52224
	ds_read_b128 v[218:221], v149 offset:53248
	ds_read_b128 v[232:235], v149 offset:54272
	ds_read_b128 v[236:239], v149 offset:55296
	ds_read_b128 v[240:243], v149 offset:56320
	global_load_lds_dwordx4 v[178:179], off
	s_add_i32 m0, s36, 0x2000
	s_add_u32 s34, s34, 0x40080
	v_lshl_add_u64 v[178:179], v[244:245], 0, s[88:89]
	s_addc_u32 s35, s35, 0
	s_add_i32 s36, s43, s51
	global_load_lds_dwordx4 v[178:179], off
	v_lshl_add_u64 v[178:179], s[34:35], 0, v[132:133]
	s_mov_b32 m0, s36
	s_nop 0
	global_load_lds_dwordx4 v[178:179], off
	v_lshl_add_u64 v[178:179], s[34:35], 0, v[136:137]
	s_add_i32 m0, s36, 0x2000
	s_nop 0
	global_load_lds_dwordx4 v[178:179], off
	v_lshl_add_u64 v[178:179], v[246:247], 0, s[88:89]
	s_mov_b32 m0, s60
	s_nop 0
	global_load_lds_dwordx4 v[178:179], off
	v_lshl_add_u64 v[178:179], v[248:249], 0, s[88:89]
	s_mov_b32 m0, s61
	s_nop 0
	global_load_lds_dwordx4 v[178:179], off
	s_waitcnt vmcnt(8)
	s_waitcnt lgkmcnt(0)
	s_barrier
	s_setprio 1
	v_mfma_f32_16x16x32_bf16 v[62:65], v[166:169], v[202:205], v[62:65]
	v_mfma_f32_16x16x32_bf16 v[58:61], v[174:177], v[202:205], v[58:61]
	v_mfma_f32_16x16x32_bf16 v[54:57], v[186:189], v[202:205], v[54:57]
	v_mfma_f32_16x16x32_bf16 v[50:53], v[194:197], v[202:205], v[50:53]
	v_mfma_f32_16x16x32_bf16 v[46:49], v[166:169], v[210:213], v[46:49]
	v_mfma_f32_16x16x32_bf16 v[42:45], v[174:177], v[210:213], v[42:45]
	v_mfma_f32_16x16x32_bf16 v[38:41], v[186:189], v[210:213], v[38:41]
	v_mfma_f32_16x16x32_bf16 v[34:37], v[194:197], v[210:213], v[34:37]
	v_mfma_f32_16x16x32_bf16 v[30:33], v[166:169], v[218:221], v[30:33]
	v_mfma_f32_16x16x32_bf16 v[26:29], v[174:177], v[218:221], v[26:29]
	v_mfma_f32_16x16x32_bf16 v[22:25], v[186:189], v[218:221], v[22:25]
	v_mfma_f32_16x16x32_bf16 v[18:21], v[194:197], v[218:221], v[18:21]
	v_mfma_f32_16x16x32_bf16 v[14:17], v[166:169], v[236:239], v[14:17]
	v_mfma_f32_16x16x32_bf16 v[10:13], v[174:177], v[236:239], v[10:13]
	v_mfma_f32_16x16x32_bf16 v[6:9], v[186:189], v[236:239], v[6:9]
	v_mfma_f32_16x16x32_bf16 v[2:5], v[194:197], v[236:239], v[2:5]
	v_mfma_f32_16x16x32_bf16 v[62:65], v[170:173], v[206:209], v[62:65]
	v_mfma_f32_16x16x32_bf16 v[58:61], v[182:185], v[206:209], v[58:61]
	v_mfma_f32_16x16x32_bf16 v[54:57], v[190:193], v[206:209], v[54:57]
	v_mfma_f32_16x16x32_bf16 v[50:53], v[198:201], v[206:209], v[50:53]
	v_mfma_f32_16x16x32_bf16 v[46:49], v[170:173], v[214:217], v[46:49]
	v_mfma_f32_16x16x32_bf16 v[42:45], v[182:185], v[214:217], v[42:45]
	v_mfma_f32_16x16x32_bf16 v[38:41], v[190:193], v[214:217], v[38:41]
	v_mfma_f32_16x16x32_bf16 v[34:37], v[198:201], v[214:217], v[34:37]
	v_mfma_f32_16x16x32_bf16 v[30:33], v[170:173], v[232:235], v[30:33]
	v_mfma_f32_16x16x32_bf16 v[26:29], v[182:185], v[232:235], v[26:29]
	v_mfma_f32_16x16x32_bf16 v[22:25], v[190:193], v[232:235], v[22:25]
	v_mfma_f32_16x16x32_bf16 v[18:21], v[198:201], v[232:235], v[18:21]
	v_mfma_f32_16x16x32_bf16 v[14:17], v[170:173], v[240:243], v[14:17]
	v_mfma_f32_16x16x32_bf16 v[10:13], v[182:185], v[240:243], v[10:13]
	v_mfma_f32_16x16x32_bf16 v[6:9], v[190:193], v[240:243], v[6:9]
	v_mfma_f32_16x16x32_bf16 v[2:5], v[198:201], v[240:243], v[2:5]
	s_setprio 0
	s_barrier
	s_add_i32 s41, s41, 2
	s_add_u32 s8, s8, 0x100
	s_addc_u32 s9, s9, 0
	s_add_u32 s39, s39, 0x100
	s_addc_u32 s40, s40, 0
	s_cmp_gt_u32 s41, 13
	s_cbranch_scc0 .LBB0_132
	s_and_b64 vcc, exec, s[16:17]
	s_cbranch_vccz .LBB0_135
	s_barrier

; #define PG8_STAGE(bufoff, gbase, voff) do { _Pragma("unroll") for (int _i = 0; _i < 2; ++_i) \
;         __builtin_amdgcn_global_load_lds((const unsigned*)((const char*)(gbase) + (voff)[_i]), (LAS unsigned*)(lds + (bufoff) + ldsw + _i * 8192), 16, 0, 0); } while (0)
; #define PG8_LDA(dst, b, h) do { _Pragma("unroll") for (int m = 0; m < 4; ++m) _Pragma("unroll") for (int k = 0; k < 2; ++k) dst[m][k] = *(const LAS bf16x8*)(lds + PG8_SA(b, h) + aoff + m * 2048 + k * 1024); } while (0)
; #define PG8_LDB(dst, b, h) do { _Pragma("unroll") for (int n = 0; n < 2; ++n) _Pragma("unroll") for (int k = 0; k < 2; ++k) dst[n][k] = *(const LAS bf16x8*)(lds + PG8_SB(b, h) + boff + n * 2048 + k * 1024); } while (0)
; #define PG8_MMA(ai, bj, At, Bt) do { __builtin_amdgcn_s_setprio(1); _Pragma("unroll") for (int m = 0; m < 4; ++m) _Pragma("unroll") for (int n = 0; n < 2; ++n) _Pragma("unroll") for (int k = 0; k < 2; ++k) \
;         acc[ai][bj][m][n] = __builtin_amdgcn_mfma_f32_16x16x32_bf16(Bt[n][k], At[m][k], acc[ai][bj][m][n], 0, 0, 0); __builtin_amdgcn_s_setprio(0); } while (0)
; #define PG8_WAIT_V(n) asm volatile("s_waitcnt vmcnt(" #n ")" ::: "memory")
; #define PG8_WAIT_L(n) asm volatile("s_waitcnt lgkmcnt(" #n ")" ::: "memory")
; #define PG8_BAR __builtin_amdgcn_s_barrier()
; #define PG8_SCHED __builtin_amdgcn_sched_barrier(0)
; template <class Epi>
; __device__ __forceinline__ void gemm_phase(LAS unsigned char* lds, const Gemm g, const StaticOrder& S, const Epi& E) {
;     ...
;         for (int t = 0; t < nt; t += 2) {
;             const bool last = (t == nt - 2);
;             const char* a1 = cA + (size_t)(t + 1) * kstep;
;             const char* a2 = last ? nA : cA + (size_t)(t + 2) * kstep; const char* b2 = last ? nB : cB + (size_t)(t + 2) * kstep;
;             const char* a3 = a2 + kstep; const char* b3 = b2 + kstep;
;             PG8_LDB(B0, 0, 0); PG8_LDB(B1, 0, 1); PG8_SCHED; PG8_LDA(At, 0, 0); PG8_STAGE(PG8_SA(1, 1), a1 + hA, voffA);
;             PG8_WAIT_V(8); PG8_WAIT_L(0); PG8_BAR; PG8_MMA(0, 0, At, B0); PG8_MMA(0, 1, At, B1); PG8_BAR; PG8_SCHED;
;             PG8_LDA(At, 0, 1); PG8_STAGE(PG8_SB(0, 0), b2, voffB); PG8_STAGE(PG8_SB(0, 1), b2 + hB, voffB); PG8_STAGE(PG8_SA(0, 0), a2, voffA);
;             PG8_WAIT_V(8); PG8_WAIT_L(0); PG8_BAR; PG8_MMA(1, 0, At, B0); PG8_MMA(1, 1, At, B1); PG8_BAR; PG8_SCHED;
.LBB0_518:
	s_add_u32 s30, s28, 0xfffc0080
	s_addc_u32 s31, s29, -1
	s_add_i32 s71, 0, 0x10000
	s_cmp_eq_u32 s70, 28
	s_cselect_b32 s35, s21, s31
	s_cselect_b32 s34, s27, s30
	v_add_u32_e32 v154, s71, v156
	s_cselect_b32 s31, s19, s67
	s_cselect_b32 s30, s65, s66
	s_add_i32 s73, 0, 0x14000
	ds_read_b128 v[98:101], v154
	ds_read_b128 v[102:105], v154 offset:1024
	ds_read_b128 v[158:161], v154 offset:2048
	ds_read_b128 v[162:165], v154 offset:3072
	v_add_u32_e32 v154, s73, v156
	ds_read_b128 v[166:169], v154
	ds_read_b128 v[170:173], v154 offset:1024
	ds_read_b128 v[174:177], v154 offset:2048
	ds_read_b128 v[182:185], v154 offset:3072
	v_lshl_add_u64 v[154:155], s[28:29], 0, v[150:151]
	s_add_i32 m0, s54, 0xc000
	ds_read_b128 v[186:189], v157
	ds_read_b128 v[190:193], v157 offset:1024
	ds_read_b128 v[194:197], v157 offset:2048
	ds_read_b128 v[198:201], v157 offset:3072
	ds_read_b128 v[202:205], v157 offset:4096
	ds_read_b128 v[206:209], v157 offset:5120
	ds_read_b128 v[210:213], v157 offset:6144
	ds_read_b128 v[214:217], v157 offset:7168
	global_load_lds_dwordx4 v[154:155], off
	v_lshl_add_u64 v[154:155], s[28:29], 0, v[152:153]
	s_add_i32 m0, s54, 0xe000
	s_nop 0
	global_load_lds_dwordx4 v[154:155], off
	s_waitcnt vmcnt(8)
	s_waitcnt lgkmcnt(0)
	s_barrier
	s_setprio 1
	v_mfma_f32_16x16x32_bf16 v[134:137], v[98:101], v[186:189], v[134:137]
	v_mfma_f32_16x16x32_bf16 v[130:133], v[158:161], v[186:189], v[130:133]
	v_mfma_f32_16x16x32_bf16 v[62:65], v[166:169], v[186:189], v[62:65]
	v_mfma_f32_16x16x32_bf16 v[58:61], v[174:177], v[186:189], v[58:61]
	v_mfma_f32_16x16x32_bf16 v[126:129], v[98:101], v[194:197], v[126:129]
	v_mfma_f32_16x16x32_bf16 v[122:125], v[158:161], v[194:197], v[122:125]
	v_mfma_f32_16x16x32_bf16 v[54:57], v[166:169], v[194:197], v[54:57]
	v_mfma_f32_16x16x32_bf16 v[50:53], v[174:177], v[194:197], v[50:53]
	v_mfma_f32_16x16x32_bf16 v[118:121], v[98:101], v[202:205], v[118:121]
	v_mfma_f32_16x16x32_bf16 v[114:117], v[158:161], v[202:205], v[114:117]
	v_mfma_f32_16x16x32_bf16 v[46:49], v[166:169], v[202:205], v[46:49]
	v_mfma_f32_16x16x32_bf16 v[42:45], v[174:177], v[202:205], v[42:45]
	v_mfma_f32_16x16x32_bf16 v[110:113], v[98:101], v[210:213], v[110:113]
	v_mfma_f32_16x16x32_bf16 v[106:109], v[158:161], v[210:213], v[106:109]
	v_mfma_f32_16x16x32_bf16 v[38:41], v[166:169], v[210:213], v[38:41]
	v_mfma_f32_16x16x32_bf16 v[34:37], v[174:177], v[210:213], v[34:37]
	v_mfma_f32_16x16x32_bf16 v[134:137], v[102:105], v[190:193], v[134:137]
	v_mfma_f32_16x16x32_bf16 v[130:133], v[162:165], v[190:193], v[130:133]
	v_mfma_f32_16x16x32_bf16 v[62:65], v[170:173], v[190:193], v[62:65]
	v_mfma_f32_16x16x32_bf16 v[58:61], v[182:185], v[190:193], v[58:61]
	v_mfma_f32_16x16x32_bf16 v[126:129], v[102:105], v[198:201], v[126:129]
	v_mfma_f32_16x16x32_bf16 v[122:125], v[162:165], v[198:201], v[122:125]
	v_mfma_f32_16x16x32_bf16 v[54:57], v[170:173], v[198:201], v[54:57]
	v_mfma_f32_16x16x32_bf16 v[50:53], v[182:185], v[198:201], v[50:53]
	v_mfma_f32_16x16x32_bf16 v[118:121], v[102:105], v[206:209], v[118:121]
	v_mfma_f32_16x16x32_bf16 v[114:117], v[162:165], v[206:209], v[114:117]
	v_mfma_f32_16x16x32_bf16 v[46:49], v[170:173], v[206:209], v[46:49]
	v_mfma_f32_16x16x32_bf16 v[42:45], v[182:185], v[206:209], v[42:45]
	v_mfma_f32_16x16x32_bf16 v[110:113], v[102:105], v[214:217], v[110:113]
	v_mfma_f32_16x16x32_bf16 v[106:109], v[162:165], v[214:217], v[106:109]
	v_mfma_f32_16x16x32_bf16 v[38:41], v[170:173], v[214:217], v[38:41]
	v_mfma_f32_16x16x32_bf16 v[34:37], v[182:185], v[214:217], v[34:37]
	s_setprio 0
	s_barrier
	s_add_i32 s71, s71, s53
	v_lshl_add_u64 v[154:155], s[30:31], 0, v[140:141]
	s_mov_b32 m0, s71
	ds_read_b128 v[186:189], v157 offset:16384
	ds_read_b128 v[190:193], v157 offset:17408
	ds_read_b128 v[194:197], v157 offset:18432
	ds_read_b128 v[198:201], v157 offset:19456
	ds_read_b128 v[202:205], v157 offset:20480
	ds_read_b128 v[206:209], v157 offset:21504
	ds_read_b128 v[210:213], v157 offset:22528
	ds_read_b128 v[214:217], v157 offset:23552
	global_load_lds_dwordx4 v[154:155], off
	s_add_i32 m0, s71, 0x2000
	s_add_u32 s74, s30, 0x80000
	v_lshl_add_u64 v[178:179], s[30:31], 0, v[144:145]
	s_addc_u32 s75, s31, 0
	s_add_i32 s71, s73, s53
	global_load_lds_dwordx4 v[178:179], off
	v_lshl_add_u64 v[218:219], s[74:75], 0, v[140:141]
	s_mov_b32 m0, s71
	v_lshl_add_u64 v[220:221], s[34:35], 0, v[142:143]
	global_load_lds_dwordx4 v[218:219], off
	v_lshl_add_u64 v[218:219], s[74:75], 0, v[144:145]
	s_add_i32 m0, s71, 0x2000
	s_nop 0
	global_load_lds_dwordx4 v[218:219], off
	v_lshl_add_u64 v[218:219], s[34:35], 0, v[138:139]
	s_mov_b32 m0, s54
	s_nop 0
	global_load_lds_dwordx4 v[218:219], off
	s_mov_b32 m0, s55
	s_nop 0
	global_load_lds_dwordx4 v[220:221], off
	s_waitcnt vmcnt(8)
	s_waitcnt lgkmcnt(0)
	s_barrier
; #define PG8_STAGE(bufoff, gbase, voff) do { _Pragma("unroll") for (int _i = 0; _i < 2; ++_i) \
;         __builtin_amdgcn_global_load_lds((const unsigned*)((const char*)(gbase) + (voff)[_i]), (LAS unsigned*)(lds + (bufoff) + ldsw + _i * 8192), 16, 0, 0); } while (0)
; #define PG8_LDA(dst, b, h) do { _Pragma("unroll") for (int m = 0; m < 4; ++m) _Pragma("unroll") for (int k = 0; k < 2; ++k) dst[m][k] = *(const LAS bf16x8*)(lds + PG8_SA(b, h) + aoff + m * 2048 + k * 1024); } while (0)
; #define PG8_LDB(dst, b, h) do { _Pragma("unroll") for (int n = 0; n < 2; ++n) _Pragma("unroll") for (int k = 0; k < 2; ++k) dst[n][k] = *(const LAS bf16x8*)(lds + PG8_SB(b, h) + boff + n * 2048 + k * 1024); } while (0)
; #define PG8_MMA(ai, bj, At, Bt) do { __builtin_amdgcn_s_setprio(1); _Pragma("unroll") for (int m = 0; m < 4; ++m) _Pragma("unroll") for (int n = 0; n < 2; ++n) _Pragma("unroll") for (int k = 0; k < 2; ++k) \
;         acc[ai][bj][m][n] = __builtin_amdgcn_mfma_f32_16x16x32_bf16(Bt[n][k], At[m][k], acc[ai][bj][m][n], 0, 0, 0); __builtin_amdgcn_s_setprio(0); } while (0)
; #define PG8_WAIT_V(n) asm volatile("s_waitcnt vmcnt(" #n ")" ::: "memory")
; #define PG8_WAIT_L(n) asm volatile("s_waitcnt lgkmcnt(" #n ")" ::: "memory")
; #define PG8_BAR __builtin_amdgcn_s_barrier()
; #define PG8_SCHED __builtin_amdgcn_sched_barrier(0)
; template <class Epi>
; __device__ __forceinline__ void gemm_phase(LAS unsigned char* lds, const Gemm g, const StaticOrder& S, const Epi& E) {
;     ...
;             PG8_WAIT_V(8); PG8_WAIT_L(0); PG8_BAR; PG8_MMA(1, 0, At, B0); PG8_MMA(1, 1, At, B1); PG8_BAR; PG8_SCHED;
;             PG8_LDB(B0, 1, 0); PG8_LDB(B1, 1, 1); PG8_SCHED; PG8_LDA(At, 1, 0); PG8_STAGE(PG8_SA(0, 1), a2 + hA, voffA);
;             PG8_WAIT_V(8); PG8_WAIT_L(0); PG8_BAR; PG8_MMA(0, 0, At, B0); PG8_MMA(0, 1, At, B1); PG8_BAR; PG8_SCHED;
	s_setprio 1
	v_mfma_f32_16x16x32_bf16 v[94:97], v[98:101], v[186:189], v[94:97]
	v_mfma_f32_16x16x32_bf16 v[90:93], v[158:161], v[186:189], v[90:93]
	v_mfma_f32_16x16x32_bf16 v[30:33], v[166:169], v[186:189], v[30:33]
	v_mfma_f32_16x16x32_bf16 v[26:29], v[174:177], v[186:189], v[26:29]
	v_mfma_f32_16x16x32_bf16 v[86:89], v[98:101], v[194:197], v[86:89]
	v_mfma_f32_16x16x32_bf16 v[82:85], v[158:161], v[194:197], v[82:85]
	v_mfma_f32_16x16x32_bf16 v[22:25], v[166:169], v[194:197], v[22:25]
	v_mfma_f32_16x16x32_bf16 v[18:21], v[174:177], v[194:197], v[18:21]
	v_mfma_f32_16x16x32_bf16 v[78:81], v[98:101], v[202:205], v[78:81]
	v_mfma_f32_16x16x32_bf16 v[74:77], v[158:161], v[202:205], v[74:77]
	v_mfma_f32_16x16x32_bf16 v[14:17], v[166:169], v[202:205], v[14:17]
	v_mfma_f32_16x16x32_bf16 v[10:13], v[174:177], v[202:205], v[10:13]
	v_mfma_f32_16x16x32_bf16 v[70:73], v[98:101], v[210:213], v[70:73]
	v_mfma_f32_16x16x32_bf16 v[66:69], v[158:161], v[210:213], v[66:69]
	v_mfma_f32_16x16x32_bf16 v[6:9], v[166:169], v[210:213], v[6:9]
	v_mfma_f32_16x16x32_bf16 v[2:5], v[174:177], v[210:213], v[2:5]
	v_mfma_f32_16x16x32_bf16 v[94:97], v[102:105], v[190:193], v[94:97]
	v_mfma_f32_16x16x32_bf16 v[90:93], v[162:165], v[190:193], v[90:93]
	v_mfma_f32_16x16x32_bf16 v[30:33], v[170:173], v[190:193], v[30:33]
	v_mfma_f32_16x16x32_bf16 v[26:29], v[182:185], v[190:193], v[26:29]
	v_mfma_f32_16x16x32_bf16 v[86:89], v[102:105], v[198:201], v[86:89]
	v_mfma_f32_16x16x32_bf16 v[82:85], v[162:165], v[198:201], v[82:85]
	v_mfma_f32_16x16x32_bf16 v[22:25], v[170:173], v[198:201], v[22:25]
	v_mfma_f32_16x16x32_bf16 v[18:21], v[182:185], v[198:201], v[18:21]
	v_mfma_f32_16x16x32_bf16 v[78:81], v[102:105], v[206:209], v[78:81]
	v_mfma_f32_16x16x32_bf16 v[74:77], v[162:165], v[206:209], v[74:77]
	v_mfma_f32_16x16x32_bf16 v[14:17], v[170:173], v[206:209], v[14:17]
	v_mfma_f32_16x16x32_bf16 v[10:13], v[182:185], v[206:209], v[10:13]
	v_mfma_f32_16x16x32_bf16 v[70:73], v[102:105], v[214:217], v[70:73]
	v_mfma_f32_16x16x32_bf16 v[66:69], v[162:165], v[214:217], v[66:69]
	v_mfma_f32_16x16x32_bf16 v[6:9], v[170:173], v[214:217], v[6:9]
	v_mfma_f32_16x16x32_bf16 v[2:5], v[182:185], v[214:217], v[2:5]
	s_setprio 0
	s_barrier
	s_add_i32 s71, 0, 0x18000
	s_add_i32 s73, 0, 0x1c000
	v_add_u32_e32 v162, s71, v156
	v_add_u32_e32 v180, s73, v156
	ds_read_b128 v[98:101], v162
	ds_read_b128 v[102:105], v162 offset:1024
	ds_read_b128 v[158:161], v162 offset:2048
	ds_read_b128 v[162:165], v162 offset:3072
	ds_read_b128 v[166:169], v180
	ds_read_b128 v[170:173], v180 offset:1024
	ds_read_b128 v[174:177], v180 offset:2048
	ds_read_b128 v[182:185], v180 offset:3072
	s_add_u32 s34, s34, 0x40000
	s_addc_u32 s35, s35, 0
	s_mov_b32 m0, s56
	v_lshl_add_u64 v[232:233], s[34:35], 0, v[138:139]
	ds_read_b128 v[186:189], v157 offset:32768
	ds_read_b128 v[190:193], v157 offset:33792
	ds_read_b128 v[194:197], v157 offset:34816
	ds_read_b128 v[198:201], v157 offset:35840
	ds_read_b128 v[202:205], v157 offset:36864
	ds_read_b128 v[206:209], v157 offset:37888
	ds_read_b128 v[210:213], v157 offset:38912
	ds_read_b128 v[214:217], v157 offset:39936
	global_load_lds_dwordx4 v[232:233], off
	v_lshl_add_u64 v[232:233], s[34:35], 0, v[142:143]
	s_mov_b32 m0, s57
	s_nop 0
	global_load_lds_dwordx4 v[232:233], off
	s_waitcnt vmcnt(8)
	s_waitcnt lgkmcnt(0)
	s_barrier
	s_setprio 1
	v_mfma_f32_16x16x32_bf16 v[134:137], v[98:101], v[186:189], v[134:137]
	v_mfma_f32_16x16x32_bf16 v[130:133], v[158:161], v[186:189], v[130:133]
	v_mfma_f32_16x16x32_bf16 v[62:65], v[166:169], v[186:189], v[62:65]
	v_mfma_f32_16x16x32_bf16 v[58:61], v[174:177], v[186:189], v[58:61]
	v_mfma_f32_16x16x32_bf16 v[126:129], v[98:101], v[194:197], v[126:129]
	v_mfma_f32_16x16x32_bf16 v[122:125], v[158:161], v[194:197], v[122:125]
	v_mfma_f32_16x16x32_bf16 v[54:57], v[166:169], v[194:197], v[54:57]
	v_mfma_f32_16x16x32_bf16 v[50:53], v[174:177], v[194:197], v[50:53]
	v_mfma_f32_16x16x32_bf16 v[118:121], v[98:101], v[202:205], v[118:121]
	v_mfma_f32_16x16x32_bf16 v[114:117], v[158:161], v[202:205], v[114:117]
	v_mfma_f32_16x16x32_bf16 v[46:49], v[166:169], v[202:205], v[46:49]
	v_mfma_f32_16x16x32_bf16 v[42:45], v[174:177], v[202:205], v[42:45]
	v_mfma_f32_16x16x32_bf16 v[110:113], v[98:101], v[210:213], v[110:113]
	v_mfma_f32_16x16x32_bf16 v[106:109], v[158:161], v[210:213], v[106:109]
	v_mfma_f32_16x16x32_bf16 v[38:41], v[166:169], v[210:213], v[38:41]
	v_mfma_f32_16x16x32_bf16 v[34:37], v[174:177], v[210:213], v[34:37]
	v_mfma_f32_16x16x32_bf16 v[134:137], v[102:105], v[190:193], v[134:137]
	v_mfma_f32_16x16x32_bf16 v[130:133], v[162:165], v[190:193], v[130:133]
	v_mfma_f32_16x16x32_bf16 v[62:65], v[170:173], v[190:193], v[62:65]
	v_mfma_f32_16x16x32_bf16 v[58:61], v[182:185], v[190:193], v[58:61]
	v_mfma_f32_16x16x32_bf16 v[126:129], v[102:105], v[198:201], v[126:129]
	v_mfma_f32_16x16x32_bf16 v[122:125], v[162:165], v[198:201], v[122:125]
	v_mfma_f32_16x16x32_bf16 v[54:57], v[170:173], v[198:201], v[54:57]
	v_mfma_f32_16x16x32_bf16 v[50:53], v[182:185], v[198:201], v[50:53]
	v_mfma_f32_16x16x32_bf16 v[118:121], v[102:105], v[206:209], v[118:121]
	v_mfma_f32_16x16x32_bf16 v[114:117], v[162:165], v[206:209], v[114:117]
	v_mfma_f32_16x16x32_bf16 v[46:49], v[170:173], v[206:209], v[46:49]
	v_mfma_f32_16x16x32_bf16 v[42:45], v[182:185], v[206:209], v[42:45]
	v_mfma_f32_16x16x32_bf16 v[110:113], v[102:105], v[214:217], v[110:113]
	v_mfma_f32_16x16x32_bf16 v[106:109], v[162:165], v[214:217], v[106:109]
	v_mfma_f32_16x16x32_bf16 v[38:41], v[170:173], v[214:217], v[38:41]
	v_mfma_f32_16x16x32_bf16 v[34:37], v[182:185], v[214:217], v[34:37]
	s_setprio 0
	s_barrier
; #define PG8_STAGE(bufoff, gbase, voff) do { _Pragma("unroll") for (int _i = 0; _i < 2; ++_i) \
;         __builtin_amdgcn_global_load_lds((const unsigned*)((const char*)(gbase) + (voff)[_i]), (LAS unsigned*)(lds + (bufoff) + ldsw + _i * 8192), 16, 0, 0); } while (0)
; #define PG8_LDA(dst, b, h) do { _Pragma("unroll") for (int m = 0; m < 4; ++m) _Pragma("unroll") for (int k = 0; k < 2; ++k) dst[m][k] = *(const LAS bf16x8*)(lds + PG8_SA(b, h) + aoff + m * 2048 + k * 1024); } while (0)
; #define PG8_MMA(ai, bj, At, Bt) do { __builtin_amdgcn_s_setprio(1); _Pragma("unroll") for (int m = 0; m < 4; ++m) _Pragma("unroll") for (int n = 0; n < 2; ++n) _Pragma("unroll") for (int k = 0; k < 2; ++k) \
;         acc[ai][bj][m][n] = __builtin_amdgcn_mfma_f32_16x16x32_bf16(Bt[n][k], At[m][k], acc[ai][bj][m][n], 0, 0, 0); __builtin_amdgcn_s_setprio(0); } while (0)
; #define PG8_WAIT_V(n) asm volatile("s_waitcnt vmcnt(" #n ")" ::: "memory")
; #define PG8_WAIT_L(n) asm volatile("s_waitcnt lgkmcnt(" #n ")" ::: "memory")
; #define PG8_BAR __builtin_amdgcn_s_barrier()
; #define PG8_SCHED __builtin_amdgcn_sched_barrier(0)
; template <class Epi>
; __device__ __forceinline__ void gemm_phase(LAS unsigned char* lds, const Gemm g, const StaticOrder& S, const Epi& E) {
;     ...
;             PG8_LDA(At, 1, 1); PG8_STAGE(PG8_SB(1, 0), b3, voffB); PG8_STAGE(PG8_SB(1, 1), b3 + hB, voffB); PG8_STAGE(PG8_SA(1, 0), a3, voffA);
;             PG8_WAIT_V(8); PG8_WAIT_L(0); PG8_BAR; PG8_MMA(1, 0, At, B0); PG8_MMA(1, 1, At, B1); PG8_BAR; PG8_SCHED;
;         }
	s_add_i32 s34, s71, s53
	v_lshl_add_u64 v[154:155], v[154:155], 0, s[88:89]
	s_mov_b32 m0, s34
	ds_read_b128 v[186:189], v157 offset:49152
	ds_read_b128 v[190:193], v157 offset:50176
	ds_read_b128 v[194:197], v157 offset:51200
	ds_read_b128 v[198:201], v157 offset:52224
	ds_read_b128 v[202:205], v157 offset:53248
	ds_read_b128 v[206:209], v157 offset:54272
	ds_read_b128 v[210:213], v157 offset:55296
	ds_read_b128 v[214:217], v157 offset:56320
	global_load_lds_dwordx4 v[154:155], off
	s_add_i32 m0, s34, 0x2000
	s_add_u32 s30, s30, 0x80080
	v_lshl_add_u64 v[154:155], v[178:179], 0, s[88:89]
	s_addc_u32 s31, s31, 0
	s_add_i32 s34, s73, s53
	global_load_lds_dwordx4 v[154:155], off
	v_lshl_add_u64 v[154:155], s[30:31], 0, v[140:141]
	s_mov_b32 m0, s34
	s_nop 0
	global_load_lds_dwordx4 v[154:155], off
	v_lshl_add_u64 v[154:155], s[30:31], 0, v[144:145]
	s_add_i32 m0, s34, 0x2000
	s_nop 0
	global_load_lds_dwordx4 v[154:155], off
	v_lshl_add_u64 v[154:155], v[218:219], 0, s[88:89]
	s_mov_b32 m0, s59
	s_nop 0
	global_load_lds_dwordx4 v[154:155], off
	v_lshl_add_u64 v[154:155], v[220:221], 0, s[88:89]
	s_mov_b32 m0, s60
	s_nop 0
	global_load_lds_dwordx4 v[154:155], off
	s_waitcnt vmcnt(8)
	s_waitcnt lgkmcnt(0)
	s_barrier
	s_setprio 1
	v_mfma_f32_16x16x32_bf16 v[94:97], v[98:101], v[186:189], v[94:97]
	v_mfma_f32_16x16x32_bf16 v[90:93], v[158:161], v[186:189], v[90:93]
	v_mfma_f32_16x16x32_bf16 v[30:33], v[166:169], v[186:189], v[30:33]
	v_mfma_f32_16x16x32_bf16 v[26:29], v[174:177], v[186:189], v[26:29]
	v_mfma_f32_16x16x32_bf16 v[86:89], v[98:101], v[194:197], v[86:89]
	v_mfma_f32_16x16x32_bf16 v[82:85], v[158:161], v[194:197], v[82:85]
	v_mfma_f32_16x16x32_bf16 v[22:25], v[166:169], v[194:197], v[22:25]
	v_mfma_f32_16x16x32_bf16 v[18:21], v[174:177], v[194:197], v[18:21]
	v_mfma_f32_16x16x32_bf16 v[78:81], v[98:101], v[202:205], v[78:81]
	v_mfma_f32_16x16x32_bf16 v[74:77], v[158:161], v[202:205], v[74:77]
	v_mfma_f32_16x16x32_bf16 v[14:17], v[166:169], v[202:205], v[14:17]
	v_mfma_f32_16x16x32_bf16 v[10:13], v[174:177], v[202:205], v[10:13]
	v_mfma_f32_16x16x32_bf16 v[70:73], v[98:101], v[210:213], v[70:73]
	v_mfma_f32_16x16x32_bf16 v[66:69], v[158:161], v[210:213], v[66:69]
	v_mfma_f32_16x16x32_bf16 v[6:9], v[166:169], v[210:213], v[6:9]
	v_mfma_f32_16x16x32_bf16 v[2:5], v[174:177], v[210:213], v[2:5]
	v_mfma_f32_16x16x32_bf16 v[94:97], v[102:105], v[190:193], v[94:97]
	v_mfma_f32_16x16x32_bf16 v[90:93], v[162:165], v[190:193], v[90:93]
	v_mfma_f32_16x16x32_bf16 v[30:33], v[170:173], v[190:193], v[30:33]
	v_mfma_f32_16x16x32_bf16 v[26:29], v[182:185], v[190:193], v[26:29]
	v_mfma_f32_16x16x32_bf16 v[86:89], v[102:105], v[198:201], v[86:89]
	v_mfma_f32_16x16x32_bf16 v[82:85], v[162:165], v[198:201], v[82:85]
	v_mfma_f32_16x16x32_bf16 v[22:25], v[170:173], v[198:201], v[22:25]
	v_mfma_f32_16x16x32_bf16 v[18:21], v[182:185], v[198:201], v[18:21]
	v_mfma_f32_16x16x32_bf16 v[78:81], v[102:105], v[206:209], v[78:81]
	v_mfma_f32_16x16x32_bf16 v[74:77], v[162:165], v[206:209], v[74:77]
	v_mfma_f32_16x16x32_bf16 v[14:17], v[170:173], v[206:209], v[14:17]
	v_mfma_f32_16x16x32_bf16 v[10:13], v[182:185], v[206:209], v[10:13]
	v_mfma_f32_16x16x32_bf16 v[70:73], v[102:105], v[214:217], v[70:73]
	v_mfma_f32_16x16x32_bf16 v[66:69], v[162:165], v[214:217], v[66:69]
	v_mfma_f32_16x16x32_bf16 v[6:9], v[170:173], v[214:217], v[6:9]
	v_mfma_f32_16x16x32_bf16 v[2:5], v[182:185], v[214:217], v[2:5]
	s_setprio 0
	s_barrier
	s_add_i32 s70, s70, 2
	s_add_u32 s28, s28, 0x100
	s_addc_u32 s29, s29, 0
	s_add_u32 s66, s66, 0x100
	s_addc_u32 s67, s67, 0
	s_cmp_gt_u32 s70, 29
	s_cbranch_scc0 .LBB0_518
	s_and_b64 vcc, exec, s[16:17]
	s_cbranch_vccz .LBB0_521
	s_barrier

; #define PG8_STAGE(bufoff, gbase, voff) do { _Pragma("unroll") for (int _i = 0; _i < 2; ++_i) \
;         __builtin_amdgcn_global_load_lds((const unsigned*)((const char*)(gbase) + (voff)[_i]), (LAS unsigned*)(lds + (bufoff) + ldsw + _i * 8192), 16, 0, 0); } while (0)
; #define PG8_LDA(dst, b, h) do { _Pragma("unroll") for (int m = 0; m < 4; ++m) _Pragma("unroll") for (int k = 0; k < 2; ++k) dst[m][k] = *(const LAS bf16x8*)(lds + PG8_SA(b, h) + aoff + m * 2048 + k * 1024); } while (0)
; #define PG8_LDB(dst, b, h) do { _Pragma("unroll") for (int n = 0; n < 2; ++n) _Pragma("unroll") for (int k = 0; k < 2; ++k) dst[n][k] = *(const LAS bf16x8*)(lds + PG8_SB(b, h) + boff + n * 2048 + k * 1024); } while (0)
; #define PG8_MMA(ai, bj, At, Bt) do { __builtin_amdgcn_s_setprio(1); _Pragma("unroll") for (int m = 0; m < 4; ++m) _Pragma("unroll") for (int n = 0; n < 2; ++n) _Pragma("unroll") for (int k = 0; k < 2; ++k) \
;         acc[ai][bj][m][n] = __builtin_amdgcn_mfma_f32_16x16x32_bf16(Bt[n][k], At[m][k], acc[ai][bj][m][n], 0, 0, 0); __builtin_amdgcn_s_setprio(0); } while (0)
; #define PG8_WAIT_V(n) asm volatile("s_waitcnt vmcnt(" #n ")" ::: "memory")
; #define PG8_WAIT_L(n) asm volatile("s_waitcnt lgkmcnt(" #n ")" ::: "memory")
; #define PG8_BAR __builtin_amdgcn_s_barrier()
; #define PG8_SCHED __builtin_amdgcn_sched_barrier(0)
; template <class Epi>
; __device__ __forceinline__ void gemm_phase(LAS unsigned char* lds, const Gemm g, const StaticOrder& S, const Epi& E) {
;     ...
;         for (int t = 0; t < nt; t += 2) {
;             const bool last = (t == nt - 2);
;             const char* a1 = cA + (size_t)(t + 1) * kstep;
;             const char* a2 = last ? nA : cA + (size_t)(t + 2) * kstep; const char* b2 = last ? nB : cB + (size_t)(t + 2) * kstep;
;             const char* a3 = a2 + kstep; const char* b3 = b2 + kstep;
;             PG8_LDB(B0, 0, 0); PG8_LDB(B1, 0, 1); PG8_SCHED; PG8_LDA(At, 0, 0); PG8_STAGE(PG8_SA(1, 1), a1 + hA, voffA);
;             PG8_WAIT_V(8); PG8_WAIT_L(0); PG8_BAR; PG8_MMA(0, 0, At, B0); PG8_MMA(0, 1, At, B1); PG8_BAR; PG8_SCHED;
;             PG8_LDA(At, 0, 1); PG8_STAGE(PG8_SB(0, 0), b2, voffB); PG8_STAGE(PG8_SB(0, 1), b2 + hB, voffB); PG8_STAGE(PG8_SA(0, 0), a2, voffA);
;             PG8_WAIT_V(8); PG8_WAIT_L(0); PG8_BAR; PG8_MMA(1, 0, At, B0); PG8_MMA(1, 1, At, B1); PG8_BAR; PG8_SCHED;
.LBB0_1398:
	s_add_u32 s10, s8, 0xfffc0080
	s_addc_u32 s11, s9, -1
	s_add_i32 s35, 0, 0x10000
	s_cmp_eq_u32 s31, 12
	s_cselect_b32 s41, s37, s11
	s_cselect_b32 s40, s36, s10
	s_cselect_b32 s11, s39, s29
	s_cselect_b32 s10, s38, s27
	s_add_i32 s64, 0, 0x14000
	v_add_u32_e32 v158, s35, v180
	v_add_u32_e32 v174, s64, v180
	ds_read_b128 v[146:149], v158
	ds_read_b128 v[150:153], v158 offset:1024
	ds_read_b128 v[154:157], v158 offset:2048
	ds_read_b128 v[158:161], v158 offset:3072
	ds_read_b128 v[162:165], v174
	ds_read_b128 v[166:169], v174 offset:1024
	ds_read_b128 v[170:173], v174 offset:2048
	ds_read_b128 v[174:177], v174 offset:3072
	v_lshl_add_u64 v[178:179], s[8:9], 0, v[142:143]
	s_add_i32 m0, s51, 0xc000
	ds_read_b128 v[182:185], v211
	ds_read_b128 v[186:189], v211 offset:1024
	ds_read_b128 v[190:193], v211 offset:2048
	ds_read_b128 v[194:197], v211 offset:3072
	ds_read_b128 v[198:201], v211 offset:4096
	ds_read_b128 v[202:205], v211 offset:5120
	ds_read_b128 v[216:219], v211 offset:6144
	ds_read_b128 v[232:235], v211 offset:7168
	global_load_lds_dwordx4 v[178:179], off
	v_lshl_add_u64 v[178:179], s[8:9], 0, v[144:145]
	s_add_i32 m0, s51, 0xe000
	s_nop 0
	global_load_lds_dwordx4 v[178:179], off
	s_waitcnt vmcnt(8)
	s_waitcnt lgkmcnt(0)
	s_barrier
	s_setprio 1
	v_mfma_f32_16x16x32_bf16 v[126:129], v[146:149], v[182:185], v[126:129]
	v_mfma_f32_16x16x32_bf16 v[122:125], v[154:157], v[182:185], v[122:125]
	v_mfma_f32_16x16x32_bf16 v[118:121], v[162:165], v[182:185], v[118:121]
	v_mfma_f32_16x16x32_bf16 v[114:117], v[170:173], v[182:185], v[114:117]
	v_mfma_f32_16x16x32_bf16 v[110:113], v[146:149], v[190:193], v[110:113]
	v_mfma_f32_16x16x32_bf16 v[106:109], v[154:157], v[190:193], v[106:109]
	v_mfma_f32_16x16x32_bf16 v[102:105], v[162:165], v[190:193], v[102:105]
	v_mfma_f32_16x16x32_bf16 v[98:101], v[170:173], v[190:193], v[98:101]
	v_mfma_f32_16x16x32_bf16 v[94:97], v[146:149], v[198:201], v[94:97]
	v_mfma_f32_16x16x32_bf16 v[90:93], v[154:157], v[198:201], v[90:93]
	v_mfma_f32_16x16x32_bf16 v[86:89], v[162:165], v[198:201], v[86:89]
	v_mfma_f32_16x16x32_bf16 v[82:85], v[170:173], v[198:201], v[82:85]
	v_mfma_f32_16x16x32_bf16 v[78:81], v[146:149], v[216:219], v[78:81]
	v_mfma_f32_16x16x32_bf16 v[74:77], v[154:157], v[216:219], v[74:77]
	v_mfma_f32_16x16x32_bf16 v[70:73], v[162:165], v[216:219], v[70:73]
	v_mfma_f32_16x16x32_bf16 v[66:69], v[170:173], v[216:219], v[66:69]
	v_mfma_f32_16x16x32_bf16 v[126:129], v[150:153], v[186:189], v[126:129]
	v_mfma_f32_16x16x32_bf16 v[122:125], v[158:161], v[186:189], v[122:125]
	v_mfma_f32_16x16x32_bf16 v[118:121], v[166:169], v[186:189], v[118:121]
	v_mfma_f32_16x16x32_bf16 v[114:117], v[174:177], v[186:189], v[114:117]
	v_mfma_f32_16x16x32_bf16 v[110:113], v[150:153], v[194:197], v[110:113]
	v_mfma_f32_16x16x32_bf16 v[106:109], v[158:161], v[194:197], v[106:109]
	v_mfma_f32_16x16x32_bf16 v[102:105], v[166:169], v[194:197], v[102:105]
	v_mfma_f32_16x16x32_bf16 v[98:101], v[174:177], v[194:197], v[98:101]
	v_mfma_f32_16x16x32_bf16 v[94:97], v[150:153], v[202:205], v[94:97]
	v_mfma_f32_16x16x32_bf16 v[90:93], v[158:161], v[202:205], v[90:93]
	v_mfma_f32_16x16x32_bf16 v[86:89], v[166:169], v[202:205], v[86:89]
	v_mfma_f32_16x16x32_bf16 v[82:85], v[174:177], v[202:205], v[82:85]
	v_mfma_f32_16x16x32_bf16 v[78:81], v[150:153], v[232:235], v[78:81]
	v_mfma_f32_16x16x32_bf16 v[74:77], v[158:161], v[232:235], v[74:77]
	v_mfma_f32_16x16x32_bf16 v[70:73], v[166:169], v[232:235], v[70:73]
	v_mfma_f32_16x16x32_bf16 v[66:69], v[174:177], v[232:235], v[66:69]
	s_setprio 0
	s_barrier
	s_add_i32 s35, s35, s50
	v_lshl_add_u64 v[178:179], s[10:11], 0, v[132:133]
	s_mov_b32 m0, s35
	ds_read_b128 v[182:185], v211 offset:16384
	ds_read_b128 v[186:189], v211 offset:17408
	ds_read_b128 v[190:193], v211 offset:18432
	ds_read_b128 v[194:197], v211 offset:19456
	ds_read_b128 v[198:201], v211 offset:20480
	ds_read_b128 v[202:205], v211 offset:21504
	ds_read_b128 v[216:219], v211 offset:22528
	ds_read_b128 v[232:235], v211 offset:23552
	global_load_lds_dwordx4 v[178:179], off
	s_add_i32 m0, s35, 0x2000
	s_add_u32 s42, s10, 0x40000
	v_lshl_add_u64 v[206:207], s[10:11], 0, v[136:137]
	s_addc_u32 s43, s11, 0
	s_add_i32 s35, s64, s50
	global_load_lds_dwordx4 v[206:207], off
	v_lshl_add_u64 v[220:221], s[42:43], 0, v[132:133]
	s_mov_b32 m0, s35
	v_lshl_add_u64 v[236:237], s[40:41], 0, v[134:135]
	global_load_lds_dwordx4 v[220:221], off
	v_lshl_add_u64 v[220:221], s[42:43], 0, v[136:137]
	s_add_i32 m0, s35, 0x2000
	s_nop 0
	global_load_lds_dwordx4 v[220:221], off
	v_lshl_add_u64 v[220:221], s[40:41], 0, v[130:131]
	s_mov_b32 m0, s51
	s_nop 0
	global_load_lds_dwordx4 v[220:221], off
	s_mov_b32 m0, s52
	s_nop 0
	global_load_lds_dwordx4 v[236:237], off
	s_waitcnt vmcnt(8)
	s_waitcnt lgkmcnt(0)
	s_barrier
; #define PG8_STAGE(bufoff, gbase, voff) do { _Pragma("unroll") for (int _i = 0; _i < 2; ++_i) \
;         __builtin_amdgcn_global_load_lds((const unsigned*)((const char*)(gbase) + (voff)[_i]), (LAS unsigned*)(lds + (bufoff) + ldsw + _i * 8192), 16, 0, 0); } while (0)
; #define PG8_LDA(dst, b, h) do { _Pragma("unroll") for (int m = 0; m < 4; ++m) _Pragma("unroll") for (int k = 0; k < 2; ++k) dst[m][k] = *(const LAS bf16x8*)(lds + PG8_SA(b, h) + aoff + m * 2048 + k * 1024); } while (0)
; #define PG8_LDB(dst, b, h) do { _Pragma("unroll") for (int n = 0; n < 2; ++n) _Pragma("unroll") for (int k = 0; k < 2; ++k) dst[n][k] = *(const LAS bf16x8*)(lds + PG8_SB(b, h) + boff + n * 2048 + k * 1024); } while (0)
; #define PG8_MMA(ai, bj, At, Bt) do { __builtin_amdgcn_s_setprio(1); _Pragma("unroll") for (int m = 0; m < 4; ++m) _Pragma("unroll") for (int n = 0; n < 2; ++n) _Pragma("unroll") for (int k = 0; k < 2; ++k) \
;         acc[ai][bj][m][n] = __builtin_amdgcn_mfma_f32_16x16x32_bf16(Bt[n][k], At[m][k], acc[ai][bj][m][n], 0, 0, 0); __builtin_amdgcn_s_setprio(0); } while (0)
; #define PG8_WAIT_V(n) asm volatile("s_waitcnt vmcnt(" #n ")" ::: "memory")
; #define PG8_WAIT_L(n) asm volatile("s_waitcnt lgkmcnt(" #n ")" ::: "memory")
; #define PG8_BAR __builtin_amdgcn_s_barrier()
; #define PG8_SCHED __builtin_amdgcn_sched_barrier(0)
; template <class Epi>
; __device__ __forceinline__ void gemm_phase(LAS unsigned char* lds, const Gemm g, const StaticOrder& S, const Epi& E) {
;     ...
;             PG8_WAIT_V(8); PG8_WAIT_L(0); PG8_BAR; PG8_MMA(1, 0, At, B0); PG8_MMA(1, 1, At, B1); PG8_BAR; PG8_SCHED;
;             PG8_LDB(B0, 1, 0); PG8_LDB(B1, 1, 1); PG8_SCHED; PG8_LDA(At, 1, 0); PG8_STAGE(PG8_SA(0, 1), a2 + hA, voffA);
;             PG8_WAIT_V(8); PG8_WAIT_L(0); PG8_BAR; PG8_MMA(0, 0, At, B0); PG8_MMA(0, 1, At, B1); PG8_BAR; PG8_SCHED;
	s_setprio 1
	v_mfma_f32_16x16x32_bf16 v[62:65], v[146:149], v[182:185], v[62:65]
	v_mfma_f32_16x16x32_bf16 v[58:61], v[154:157], v[182:185], v[58:61]
	v_mfma_f32_16x16x32_bf16 v[54:57], v[162:165], v[182:185], v[54:57]
	v_mfma_f32_16x16x32_bf16 v[50:53], v[170:173], v[182:185], v[50:53]
	v_mfma_f32_16x16x32_bf16 v[46:49], v[146:149], v[190:193], v[46:49]
	v_mfma_f32_16x16x32_bf16 v[42:45], v[154:157], v[190:193], v[42:45]
	v_mfma_f32_16x16x32_bf16 v[38:41], v[162:165], v[190:193], v[38:41]
	v_mfma_f32_16x16x32_bf16 v[34:37], v[170:173], v[190:193], v[34:37]
	v_mfma_f32_16x16x32_bf16 v[30:33], v[146:149], v[198:201], v[30:33]
	v_mfma_f32_16x16x32_bf16 v[26:29], v[154:157], v[198:201], v[26:29]
	v_mfma_f32_16x16x32_bf16 v[22:25], v[162:165], v[198:201], v[22:25]
	v_mfma_f32_16x16x32_bf16 v[18:21], v[170:173], v[198:201], v[18:21]
	v_mfma_f32_16x16x32_bf16 v[14:17], v[146:149], v[216:219], v[14:17]
	v_mfma_f32_16x16x32_bf16 v[10:13], v[154:157], v[216:219], v[10:13]
	v_mfma_f32_16x16x32_bf16 v[6:9], v[162:165], v[216:219], v[6:9]
	v_mfma_f32_16x16x32_bf16 v[2:5], v[170:173], v[216:219], v[2:5]
	v_mfma_f32_16x16x32_bf16 v[62:65], v[150:153], v[186:189], v[62:65]
	v_mfma_f32_16x16x32_bf16 v[58:61], v[158:161], v[186:189], v[58:61]
	v_mfma_f32_16x16x32_bf16 v[54:57], v[166:169], v[186:189], v[54:57]
	v_mfma_f32_16x16x32_bf16 v[50:53], v[174:177], v[186:189], v[50:53]
	v_mfma_f32_16x16x32_bf16 v[46:49], v[150:153], v[194:197], v[46:49]
	v_mfma_f32_16x16x32_bf16 v[42:45], v[158:161], v[194:197], v[42:45]
	v_mfma_f32_16x16x32_bf16 v[38:41], v[166:169], v[194:197], v[38:41]
	v_mfma_f32_16x16x32_bf16 v[34:37], v[174:177], v[194:197], v[34:37]
	v_mfma_f32_16x16x32_bf16 v[30:33], v[150:153], v[202:205], v[30:33]
	v_mfma_f32_16x16x32_bf16 v[26:29], v[158:161], v[202:205], v[26:29]
	v_mfma_f32_16x16x32_bf16 v[22:25], v[166:169], v[202:205], v[22:25]
	v_mfma_f32_16x16x32_bf16 v[18:21], v[174:177], v[202:205], v[18:21]
	v_mfma_f32_16x16x32_bf16 v[14:17], v[150:153], v[232:235], v[14:17]
	v_mfma_f32_16x16x32_bf16 v[10:13], v[158:161], v[232:235], v[10:13]
	v_mfma_f32_16x16x32_bf16 v[6:9], v[166:169], v[232:235], v[6:9]
	v_mfma_f32_16x16x32_bf16 v[2:5], v[174:177], v[232:235], v[2:5]
	s_setprio 0
	s_barrier
	s_add_i32 s35, 0, 0x18000
	s_add_i32 s42, 0, 0x1c000
	v_add_u32_e32 v158, s35, v180
	v_add_u32_e32 v174, s42, v180
	ds_read_b128 v[146:149], v158
	ds_read_b128 v[150:153], v158 offset:1024
	ds_read_b128 v[154:157], v158 offset:2048
	ds_read_b128 v[158:161], v158 offset:3072
	ds_read_b128 v[162:165], v174
	ds_read_b128 v[166:169], v174 offset:1024
	ds_read_b128 v[170:173], v174 offset:2048
	ds_read_b128 v[174:177], v174 offset:3072
	s_add_u32 s40, s40, 0x40000
	s_addc_u32 s41, s41, 0
	s_mov_b32 m0, s53
	v_lshl_add_u64 v[238:239], s[40:41], 0, v[130:131]
	ds_read_b128 v[182:185], v211 offset:32768
	ds_read_b128 v[186:189], v211 offset:33792
	ds_read_b128 v[190:193], v211 offset:34816
	ds_read_b128 v[194:197], v211 offset:35840
	ds_read_b128 v[198:201], v211 offset:36864
	ds_read_b128 v[202:205], v211 offset:37888
	ds_read_b128 v[216:219], v211 offset:38912
	ds_read_b128 v[232:235], v211 offset:39936
	global_load_lds_dwordx4 v[238:239], off
	v_lshl_add_u64 v[238:239], s[40:41], 0, v[134:135]
	s_mov_b32 m0, s54
	s_nop 0
	global_load_lds_dwordx4 v[238:239], off
	s_waitcnt vmcnt(8)
	s_waitcnt lgkmcnt(0)
	s_barrier
	s_setprio 1
	v_mfma_f32_16x16x32_bf16 v[126:129], v[146:149], v[182:185], v[126:129]
	v_mfma_f32_16x16x32_bf16 v[122:125], v[154:157], v[182:185], v[122:125]
	v_mfma_f32_16x16x32_bf16 v[118:121], v[162:165], v[182:185], v[118:121]
	v_mfma_f32_16x16x32_bf16 v[114:117], v[170:173], v[182:185], v[114:117]
	v_mfma_f32_16x16x32_bf16 v[110:113], v[146:149], v[190:193], v[110:113]
	v_mfma_f32_16x16x32_bf16 v[106:109], v[154:157], v[190:193], v[106:109]
	v_mfma_f32_16x16x32_bf16 v[102:105], v[162:165], v[190:193], v[102:105]
	v_mfma_f32_16x16x32_bf16 v[98:101], v[170:173], v[190:193], v[98:101]
	v_mfma_f32_16x16x32_bf16 v[94:97], v[146:149], v[198:201], v[94:97]
	v_mfma_f32_16x16x32_bf16 v[90:93], v[154:157], v[198:201], v[90:93]
	v_mfma_f32_16x16x32_bf16 v[86:89], v[162:165], v[198:201], v[86:89]
	v_mfma_f32_16x16x32_bf16 v[82:85], v[170:173], v[198:201], v[82:85]
	v_mfma_f32_16x16x32_bf16 v[78:81], v[146:149], v[216:219], v[78:81]
	v_mfma_f32_16x16x32_bf16 v[74:77], v[154:157], v[216:219], v[74:77]
	v_mfma_f32_16x16x32_bf16 v[70:73], v[162:165], v[216:219], v[70:73]
	v_mfma_f32_16x16x32_bf16 v[66:69], v[170:173], v[216:219], v[66:69]
	v_mfma_f32_16x16x32_bf16 v[126:129], v[150:153], v[186:189], v[126:129]
	v_mfma_f32_16x16x32_bf16 v[122:125], v[158:161], v[186:189], v[122:125]
	v_mfma_f32_16x16x32_bf16 v[118:121], v[166:169], v[186:189], v[118:121]
	v_mfma_f32_16x16x32_bf16 v[114:117], v[174:177], v[186:189], v[114:117]
	v_mfma_f32_16x16x32_bf16 v[110:113], v[150:153], v[194:197], v[110:113]
	v_mfma_f32_16x16x32_bf16 v[106:109], v[158:161], v[194:197], v[106:109]
	v_mfma_f32_16x16x32_bf16 v[102:105], v[166:169], v[194:197], v[102:105]
	v_mfma_f32_16x16x32_bf16 v[98:101], v[174:177], v[194:197], v[98:101]
	v_mfma_f32_16x16x32_bf16 v[94:97], v[150:153], v[202:205], v[94:97]
	v_mfma_f32_16x16x32_bf16 v[90:93], v[158:161], v[202:205], v[90:93]
	v_mfma_f32_16x16x32_bf16 v[86:89], v[166:169], v[202:205], v[86:89]
	v_mfma_f32_16x16x32_bf16 v[82:85], v[174:177], v[202:205], v[82:85]
	v_mfma_f32_16x16x32_bf16 v[78:81], v[150:153], v[232:235], v[78:81]
	v_mfma_f32_16x16x32_bf16 v[74:77], v[158:161], v[232:235], v[74:77]
	v_mfma_f32_16x16x32_bf16 v[70:73], v[166:169], v[232:235], v[70:73]
	v_mfma_f32_16x16x32_bf16 v[66:69], v[174:177], v[232:235], v[66:69]
	s_setprio 0
	s_barrier
; #define PG8_STAGE(bufoff, gbase, voff) do { _Pragma("unroll") for (int _i = 0; _i < 2; ++_i) \
;         __builtin_amdgcn_global_load_lds((const unsigned*)((const char*)(gbase) + (voff)[_i]), (LAS unsigned*)(lds + (bufoff) + ldsw + _i * 8192), 16, 0, 0); } while (0)
; #define PG8_LDA(dst, b, h) do { _Pragma("unroll") for (int m = 0; m < 4; ++m) _Pragma("unroll") for (int k = 0; k < 2; ++k) dst[m][k] = *(const LAS bf16x8*)(lds + PG8_SA(b, h) + aoff + m * 2048 + k * 1024); } while (0)
; #define PG8_MMA(ai, bj, At, Bt) do { __builtin_amdgcn_s_setprio(1); _Pragma("unroll") for (int m = 0; m < 4; ++m) _Pragma("unroll") for (int n = 0; n < 2; ++n) _Pragma("unroll") for (int k = 0; k < 2; ++k) \
;         acc[ai][bj][m][n] = __builtin_amdgcn_mfma_f32_16x16x32_bf16(Bt[n][k], At[m][k], acc[ai][bj][m][n], 0, 0, 0); __builtin_amdgcn_s_setprio(0); } while (0)
; #define PG8_WAIT_V(n) asm volatile("s_waitcnt vmcnt(" #n ")" ::: "memory")
; #define PG8_WAIT_L(n) asm volatile("s_waitcnt lgkmcnt(" #n ")" ::: "memory")
; #define PG8_BAR __builtin_amdgcn_s_barrier()
; #define PG8_SCHED __builtin_amdgcn_sched_barrier(0)
; template <class Epi>
; __device__ __forceinline__ void gemm_phase(LAS unsigned char* lds, const Gemm g, const StaticOrder& S, const Epi& E) {
;     ...
;             PG8_LDA(At, 1, 1); PG8_STAGE(PG8_SB(1, 0), b3, voffB); PG8_STAGE(PG8_SB(1, 1), b3 + hB, voffB); PG8_STAGE(PG8_SA(1, 0), a3, voffA);
;             PG8_WAIT_V(8); PG8_WAIT_L(0); PG8_BAR; PG8_MMA(1, 0, At, B0); PG8_MMA(1, 1, At, B1); PG8_BAR; PG8_SCHED;
;         }
	s_add_i32 s35, s35, s50
	v_lshl_add_u64 v[178:179], v[178:179], 0, s[88:89]
	s_mov_b32 m0, s35
	ds_read_b128 v[182:185], v211 offset:49152
	ds_read_b128 v[186:189], v211 offset:50176
	ds_read_b128 v[190:193], v211 offset:51200
	ds_read_b128 v[194:197], v211 offset:52224
	ds_read_b128 v[198:201], v211 offset:53248
	ds_read_b128 v[202:205], v211 offset:54272
	ds_read_b128 v[216:219], v211 offset:55296
	ds_read_b128 v[232:235], v211 offset:56320
	global_load_lds_dwordx4 v[178:179], off
	s_add_i32 m0, s35, 0x2000
	s_add_u32 s10, s10, 0x40080
	v_lshl_add_u64 v[178:179], v[206:207], 0, s[88:89]
	s_addc_u32 s11, s11, 0
	s_add_i32 s35, s42, s50
	global_load_lds_dwordx4 v[178:179], off
	v_lshl_add_u64 v[178:179], s[10:11], 0, v[132:133]
	s_mov_b32 m0, s35
	s_nop 0
	global_load_lds_dwordx4 v[178:179], off
	v_lshl_add_u64 v[178:179], s[10:11], 0, v[136:137]
	s_add_i32 m0, s35, 0x2000
	s_nop 0
	global_load_lds_dwordx4 v[178:179], off
	v_lshl_add_u64 v[178:179], v[220:221], 0, s[88:89]
	s_mov_b32 m0, s55
	s_nop 0
	global_load_lds_dwordx4 v[178:179], off
	v_lshl_add_u64 v[178:179], v[236:237], 0, s[88:89]
	s_mov_b32 m0, s56
	s_nop 0
	global_load_lds_dwordx4 v[178:179], off
	s_waitcnt vmcnt(8)
	s_waitcnt lgkmcnt(0)
	s_barrier
	s_setprio 1
	v_mfma_f32_16x16x32_bf16 v[62:65], v[146:149], v[182:185], v[62:65]
	v_mfma_f32_16x16x32_bf16 v[58:61], v[154:157], v[182:185], v[58:61]
	v_mfma_f32_16x16x32_bf16 v[54:57], v[162:165], v[182:185], v[54:57]
	v_mfma_f32_16x16x32_bf16 v[50:53], v[170:173], v[182:185], v[50:53]
	v_mfma_f32_16x16x32_bf16 v[46:49], v[146:149], v[190:193], v[46:49]
	v_mfma_f32_16x16x32_bf16 v[42:45], v[154:157], v[190:193], v[42:45]
	v_mfma_f32_16x16x32_bf16 v[38:41], v[162:165], v[190:193], v[38:41]
	v_mfma_f32_16x16x32_bf16 v[34:37], v[170:173], v[190:193], v[34:37]
	v_mfma_f32_16x16x32_bf16 v[30:33], v[146:149], v[198:201], v[30:33]
	v_mfma_f32_16x16x32_bf16 v[26:29], v[154:157], v[198:201], v[26:29]
	v_mfma_f32_16x16x32_bf16 v[22:25], v[162:165], v[198:201], v[22:25]
	v_mfma_f32_16x16x32_bf16 v[18:21], v[170:173], v[198:201], v[18:21]
	v_mfma_f32_16x16x32_bf16 v[14:17], v[146:149], v[216:219], v[14:17]
	v_mfma_f32_16x16x32_bf16 v[10:13], v[154:157], v[216:219], v[10:13]
	v_mfma_f32_16x16x32_bf16 v[6:9], v[162:165], v[216:219], v[6:9]
	v_mfma_f32_16x16x32_bf16 v[2:5], v[170:173], v[216:219], v[2:5]
	v_mfma_f32_16x16x32_bf16 v[62:65], v[150:153], v[186:189], v[62:65]
	v_mfma_f32_16x16x32_bf16 v[58:61], v[158:161], v[186:189], v[58:61]
	v_mfma_f32_16x16x32_bf16 v[54:57], v[166:169], v[186:189], v[54:57]
	v_mfma_f32_16x16x32_bf16 v[50:53], v[174:177], v[186:189], v[50:53]
	v_mfma_f32_16x16x32_bf16 v[46:49], v[150:153], v[194:197], v[46:49]
	v_mfma_f32_16x16x32_bf16 v[42:45], v[158:161], v[194:197], v[42:45]
	v_mfma_f32_16x16x32_bf16 v[38:41], v[166:169], v[194:197], v[38:41]
	v_mfma_f32_16x16x32_bf16 v[34:37], v[174:177], v[194:197], v[34:37]
	v_mfma_f32_16x16x32_bf16 v[30:33], v[150:153], v[202:205], v[30:33]
	v_mfma_f32_16x16x32_bf16 v[26:29], v[158:161], v[202:205], v[26:29]
	v_mfma_f32_16x16x32_bf16 v[22:25], v[166:169], v[202:205], v[22:25]
	v_mfma_f32_16x16x32_bf16 v[18:21], v[174:177], v[202:205], v[18:21]
	v_mfma_f32_16x16x32_bf16 v[14:17], v[150:153], v[232:235], v[14:17]
	v_mfma_f32_16x16x32_bf16 v[10:13], v[158:161], v[232:235], v[10:13]
	v_mfma_f32_16x16x32_bf16 v[6:9], v[166:169], v[232:235], v[6:9]
	v_mfma_f32_16x16x32_bf16 v[2:5], v[174:177], v[232:235], v[2:5]
	s_setprio 0
	s_barrier
	s_add_i32 s31, s31, 2
	s_add_u32 s8, s8, 0x100
	s_addc_u32 s9, s9, 0
	s_add_u32 s27, s27, 0x100
	s_addc_u32 s29, s29, 0
	s_cmp_gt_u32 s31, 13
	s_cbranch_scc0 .LBB0_1398
	s_and_b64 vcc, exec, s[16:17]
	s_cbranch_vccz .LBB0_1401
	s_barrier

; #define PG8_STAGE(bufoff, gbase, voff) do { _Pragma("unroll") for (int _i = 0; _i < 2; ++_i) \
;         __builtin_amdgcn_global_load_lds((const unsigned*)((const char*)(gbase) + (voff)[_i]), (LAS unsigned*)(lds + (bufoff) + ldsw + _i * 8192), 16, 0, 0); } while (0)
; #define PG8_LDA(dst, b, h) do { _Pragma("unroll") for (int m = 0; m < 4; ++m) _Pragma("unroll") for (int k = 0; k < 2; ++k) dst[m][k] = *(const LAS bf16x8*)(lds + PG8_SA(b, h) + aoff + m * 2048 + k * 1024); } while (0)
; #define PG8_LDB(dst, b, h) do { _Pragma("unroll") for (int n = 0; n < 2; ++n) _Pragma("unroll") for (int k = 0; k < 2; ++k) dst[n][k] = *(const LAS bf16x8*)(lds + PG8_SB(b, h) + boff + n * 2048 + k * 1024); } while (0)
; #define PG8_MMA(ai, bj, At, Bt) do { __builtin_amdgcn_s_setprio(1); _Pragma("unroll") for (int m = 0; m < 4; ++m) _Pragma("unroll") for (int n = 0; n < 2; ++n) _Pragma("unroll") for (int k = 0; k < 2; ++k) \
;         acc[ai][bj][m][n] = __builtin_amdgcn_mfma_f32_16x16x32_bf16(Bt[n][k], At[m][k], acc[ai][bj][m][n], 0, 0, 0); __builtin_amdgcn_s_setprio(0); } while (0)
; #define PG8_WAIT_V(n) asm volatile("s_waitcnt vmcnt(" #n ")" ::: "memory")
; #define PG8_WAIT_L(n) asm volatile("s_waitcnt lgkmcnt(" #n ")" ::: "memory")
; #define PG8_BAR __builtin_amdgcn_s_barrier()
; #define PG8_SCHED __builtin_amdgcn_sched_barrier(0)
; template <class Epi>
; __device__ __forceinline__ void gemm_phase(LAS unsigned char* lds, const Gemm g, const StaticOrder& S, const Epi& E) {
;     ...
;         for (int t = 0; t < nt; t += 2) {
;             const bool last = (t == nt - 2);
;             const char* a1 = cA + (size_t)(t + 1) * kstep;
;             const char* a2 = last ? nA : cA + (size_t)(t + 2) * kstep; const char* b2 = last ? nB : cB + (size_t)(t + 2) * kstep;
;             const char* a3 = a2 + kstep; const char* b3 = b2 + kstep;
;             PG8_LDB(B0, 0, 0); PG8_LDB(B1, 0, 1); PG8_SCHED; PG8_LDA(At, 0, 0); PG8_STAGE(PG8_SA(1, 1), a1 + hA, voffA);
;             PG8_WAIT_V(8); PG8_WAIT_L(0); PG8_BAR; PG8_MMA(0, 0, At, B0); PG8_MMA(0, 1, At, B1); PG8_BAR; PG8_SCHED;
;             PG8_LDA(At, 0, 1); PG8_STAGE(PG8_SB(0, 0), b2, voffB); PG8_STAGE(PG8_SB(0, 1), b2 + hB, voffB); PG8_STAGE(PG8_SA(0, 0), a2, voffA);
;             PG8_WAIT_V(8); PG8_WAIT_L(0); PG8_BAR; PG8_MMA(1, 0, At, B0); PG8_MMA(1, 1, At, B1); PG8_BAR; PG8_SCHED;
.LBB0_1550:
	s_add_u32 s22, s20, 0xfffc0080
	s_addc_u32 s23, s21, -1
	s_add_i32 s51, 0, 0x10000
	s_cmp_eq_u32 s50, 12
	s_cselect_b32 s25, s15, s23
	s_cselect_b32 s24, s46, s22
	v_add_u32_e32 v142, s51, v143
	s_cselect_b32 s23, s13, s49
	s_cselect_b32 s22, s47, s48
	s_add_i32 s54, 0, 0x14000
	ds_read_b128 v[148:151], v142
	ds_read_b128 v[152:155], v142 offset:1024
	ds_read_b128 v[156:159], v142 offset:2048
	ds_read_b128 v[160:163], v142 offset:3072
	v_add_u32_e32 v142, s54, v143
	ds_read_b128 v[164:167], v142
	ds_read_b128 v[168:171], v142 offset:1024
	ds_read_b128 v[172:175], v142 offset:2048
	ds_read_b128 v[176:179], v142 offset:3072
	v_lshl_add_u64 v[214:215], s[20:21], 0, v[138:139]
	s_add_i32 m0, s34, 0xc000
	ds_read_b128 v[182:185], v147
	ds_read_b128 v[186:189], v147 offset:1024
	ds_read_b128 v[190:193], v147 offset:2048
	ds_read_b128 v[194:197], v147 offset:3072
	ds_read_b128 v[198:201], v147 offset:4096
	ds_read_b128 v[202:205], v147 offset:5120
	ds_read_b128 v[206:209], v147 offset:6144
	ds_read_b128 v[210:213], v147 offset:7168
	global_load_lds_dwordx4 v[214:215], off
	v_lshl_add_u64 v[214:215], s[20:21], 0, v[140:141]
	s_add_i32 m0, s34, 0xe000
	s_nop 0
	global_load_lds_dwordx4 v[214:215], off
	s_waitcnt vmcnt(8)
	s_waitcnt lgkmcnt(0)
	s_barrier
	s_setprio 1
	v_mfma_f32_16x16x32_bf16 v[126:129], v[148:151], v[182:185], v[126:129]
	v_mfma_f32_16x16x32_bf16 v[122:125], v[156:159], v[182:185], v[122:125]
	v_mfma_f32_16x16x32_bf16 v[118:121], v[164:167], v[182:185], v[118:121]
	v_mfma_f32_16x16x32_bf16 v[114:117], v[172:175], v[182:185], v[114:117]
	v_mfma_f32_16x16x32_bf16 v[110:113], v[148:151], v[190:193], v[110:113]
	v_mfma_f32_16x16x32_bf16 v[106:109], v[156:159], v[190:193], v[106:109]
	v_mfma_f32_16x16x32_bf16 v[102:105], v[164:167], v[190:193], v[102:105]
	v_mfma_f32_16x16x32_bf16 v[98:101], v[172:175], v[190:193], v[98:101]
	v_mfma_f32_16x16x32_bf16 v[94:97], v[148:151], v[198:201], v[94:97]
	v_mfma_f32_16x16x32_bf16 v[90:93], v[156:159], v[198:201], v[90:93]
	v_mfma_f32_16x16x32_bf16 v[86:89], v[164:167], v[198:201], v[86:89]
	v_mfma_f32_16x16x32_bf16 v[82:85], v[172:175], v[198:201], v[82:85]
	v_mfma_f32_16x16x32_bf16 v[78:81], v[148:151], v[206:209], v[78:81]
	v_mfma_f32_16x16x32_bf16 v[74:77], v[156:159], v[206:209], v[74:77]
	v_mfma_f32_16x16x32_bf16 v[70:73], v[164:167], v[206:209], v[70:73]
	v_mfma_f32_16x16x32_bf16 v[66:69], v[172:175], v[206:209], v[66:69]
	v_mfma_f32_16x16x32_bf16 v[126:129], v[152:155], v[186:189], v[126:129]
	v_mfma_f32_16x16x32_bf16 v[122:125], v[160:163], v[186:189], v[122:125]
	v_mfma_f32_16x16x32_bf16 v[118:121], v[168:171], v[186:189], v[118:121]
	v_mfma_f32_16x16x32_bf16 v[114:117], v[176:179], v[186:189], v[114:117]
	v_mfma_f32_16x16x32_bf16 v[110:113], v[152:155], v[194:197], v[110:113]
	v_mfma_f32_16x16x32_bf16 v[106:109], v[160:163], v[194:197], v[106:109]
	v_mfma_f32_16x16x32_bf16 v[102:105], v[168:171], v[194:197], v[102:105]
	v_mfma_f32_16x16x32_bf16 v[98:101], v[176:179], v[194:197], v[98:101]
	v_mfma_f32_16x16x32_bf16 v[94:97], v[152:155], v[202:205], v[94:97]
	v_mfma_f32_16x16x32_bf16 v[90:93], v[160:163], v[202:205], v[90:93]
	v_mfma_f32_16x16x32_bf16 v[86:89], v[168:171], v[202:205], v[86:89]
	v_mfma_f32_16x16x32_bf16 v[82:85], v[176:179], v[202:205], v[82:85]
	v_mfma_f32_16x16x32_bf16 v[78:81], v[152:155], v[210:213], v[78:81]
	v_mfma_f32_16x16x32_bf16 v[74:77], v[160:163], v[210:213], v[74:77]
	v_mfma_f32_16x16x32_bf16 v[70:73], v[168:171], v[210:213], v[70:73]
	v_mfma_f32_16x16x32_bf16 v[66:69], v[176:179], v[210:213], v[66:69]
	s_setprio 0
	s_barrier
	s_add_i32 s51, s51, s31
	v_lshl_add_u64 v[214:215], s[22:23], 0, v[134:135]
	s_mov_b32 m0, s51
	ds_read_b128 v[182:185], v147 offset:16384
	ds_read_b128 v[186:189], v147 offset:17408
	ds_read_b128 v[190:193], v147 offset:18432
	ds_read_b128 v[194:197], v147 offset:19456
	ds_read_b128 v[198:201], v147 offset:20480
	ds_read_b128 v[202:205], v147 offset:21504
	ds_read_b128 v[206:209], v147 offset:22528
	ds_read_b128 v[210:213], v147 offset:23552
	global_load_lds_dwordx4 v[214:215], off
	s_add_i32 m0, s51, 0x2000
	s_add_u32 s52, s22, 0x40000
	v_lshl_add_u64 v[216:217], s[22:23], 0, v[130:131]
	s_addc_u32 s53, s23, 0
	s_add_i32 s51, s54, s31
	global_load_lds_dwordx4 v[216:217], off
	v_lshl_add_u64 v[218:219], s[52:53], 0, v[134:135]
	s_mov_b32 m0, s51
	v_lshl_add_u64 v[220:221], s[24:25], 0, v[132:133]
	global_load_lds_dwordx4 v[218:219], off
	v_lshl_add_u64 v[218:219], s[52:53], 0, v[130:131]
	s_add_i32 m0, s51, 0x2000
	s_nop 0
	global_load_lds_dwordx4 v[218:219], off
	v_lshl_add_u64 v[218:219], s[24:25], 0, v[136:137]
	s_mov_b32 m0, s34
	s_nop 0
	global_load_lds_dwordx4 v[218:219], off
	s_mov_b32 m0, s35
	s_nop 0
	global_load_lds_dwordx4 v[220:221], off
	s_waitcnt vmcnt(8)
	s_waitcnt lgkmcnt(0)
	s_barrier
; #define PG8_STAGE(bufoff, gbase, voff) do { _Pragma("unroll") for (int _i = 0; _i < 2; ++_i) \
;         __builtin_amdgcn_global_load_lds((const unsigned*)((const char*)(gbase) + (voff)[_i]), (LAS unsigned*)(lds + (bufoff) + ldsw + _i * 8192), 16, 0, 0); } while (0)
; #define PG8_LDA(dst, b, h) do { _Pragma("unroll") for (int m = 0; m < 4; ++m) _Pragma("unroll") for (int k = 0; k < 2; ++k) dst[m][k] = *(const LAS bf16x8*)(lds + PG8_SA(b, h) + aoff + m * 2048 + k * 1024); } while (0)
; #define PG8_LDB(dst, b, h) do { _Pragma("unroll") for (int n = 0; n < 2; ++n) _Pragma("unroll") for (int k = 0; k < 2; ++k) dst[n][k] = *(const LAS bf16x8*)(lds + PG8_SB(b, h) + boff + n * 2048 + k * 1024); } while (0)
; #define PG8_MMA(ai, bj, At, Bt) do { __builtin_amdgcn_s_setprio(1); _Pragma("unroll") for (int m = 0; m < 4; ++m) _Pragma("unroll") for (int n = 0; n < 2; ++n) _Pragma("unroll") for (int k = 0; k < 2; ++k) \
;         acc[ai][bj][m][n] = __builtin_amdgcn_mfma_f32_16x16x32_bf16(Bt[n][k], At[m][k], acc[ai][bj][m][n], 0, 0, 0); __builtin_amdgcn_s_setprio(0); } while (0)
; #define PG8_WAIT_V(n) asm volatile("s_waitcnt vmcnt(" #n ")" ::: "memory")
; #define PG8_WAIT_L(n) asm volatile("s_waitcnt lgkmcnt(" #n ")" ::: "memory")
; #define PG8_BAR __builtin_amdgcn_s_barrier()
; #define PG8_SCHED __builtin_amdgcn_sched_barrier(0)
; template <class Epi>
; __device__ __forceinline__ void gemm_phase(LAS unsigned char* lds, const Gemm g, const StaticOrder& S, const Epi& E) {
;     ...
;             PG8_WAIT_V(8); PG8_WAIT_L(0); PG8_BAR; PG8_MMA(1, 0, At, B0); PG8_MMA(1, 1, At, B1); PG8_BAR; PG8_SCHED;
;             PG8_LDB(B0, 1, 0); PG8_LDB(B1, 1, 1); PG8_SCHED; PG8_LDA(At, 1, 0); PG8_STAGE(PG8_SA(0, 1), a2 + hA, voffA);
;             PG8_WAIT_V(8); PG8_WAIT_L(0); PG8_BAR; PG8_MMA(0, 0, At, B0); PG8_MMA(0, 1, At, B1); PG8_BAR; PG8_SCHED;
	s_setprio 1
	v_mfma_f32_16x16x32_bf16 v[62:65], v[148:151], v[182:185], v[62:65]
	v_mfma_f32_16x16x32_bf16 v[58:61], v[156:159], v[182:185], v[58:61]
	v_mfma_f32_16x16x32_bf16 v[54:57], v[164:167], v[182:185], v[54:57]
	v_mfma_f32_16x16x32_bf16 v[50:53], v[172:175], v[182:185], v[50:53]
	v_mfma_f32_16x16x32_bf16 v[46:49], v[148:151], v[190:193], v[46:49]
	v_mfma_f32_16x16x32_bf16 v[42:45], v[156:159], v[190:193], v[42:45]
	v_mfma_f32_16x16x32_bf16 v[38:41], v[164:167], v[190:193], v[38:41]
	v_mfma_f32_16x16x32_bf16 v[34:37], v[172:175], v[190:193], v[34:37]
	v_mfma_f32_16x16x32_bf16 v[30:33], v[148:151], v[198:201], v[30:33]
	v_mfma_f32_16x16x32_bf16 v[26:29], v[156:159], v[198:201], v[26:29]
	v_mfma_f32_16x16x32_bf16 v[22:25], v[164:167], v[198:201], v[22:25]
	v_mfma_f32_16x16x32_bf16 v[18:21], v[172:175], v[198:201], v[18:21]
	v_mfma_f32_16x16x32_bf16 v[14:17], v[148:151], v[206:209], v[14:17]
	v_mfma_f32_16x16x32_bf16 v[10:13], v[156:159], v[206:209], v[10:13]
	v_mfma_f32_16x16x32_bf16 v[6:9], v[164:167], v[206:209], v[6:9]
	v_mfma_f32_16x16x32_bf16 v[2:5], v[172:175], v[206:209], v[2:5]
	v_mfma_f32_16x16x32_bf16 v[62:65], v[152:155], v[186:189], v[62:65]
	v_mfma_f32_16x16x32_bf16 v[58:61], v[160:163], v[186:189], v[58:61]
	v_mfma_f32_16x16x32_bf16 v[54:57], v[168:171], v[186:189], v[54:57]
	v_mfma_f32_16x16x32_bf16 v[50:53], v[176:179], v[186:189], v[50:53]
	v_mfma_f32_16x16x32_bf16 v[46:49], v[152:155], v[194:197], v[46:49]
	v_mfma_f32_16x16x32_bf16 v[42:45], v[160:163], v[194:197], v[42:45]
	v_mfma_f32_16x16x32_bf16 v[38:41], v[168:171], v[194:197], v[38:41]
	v_mfma_f32_16x16x32_bf16 v[34:37], v[176:179], v[194:197], v[34:37]
	v_mfma_f32_16x16x32_bf16 v[30:33], v[152:155], v[202:205], v[30:33]
	v_mfma_f32_16x16x32_bf16 v[26:29], v[160:163], v[202:205], v[26:29]
	v_mfma_f32_16x16x32_bf16 v[22:25], v[168:171], v[202:205], v[22:25]
	v_mfma_f32_16x16x32_bf16 v[18:21], v[176:179], v[202:205], v[18:21]
	v_mfma_f32_16x16x32_bf16 v[14:17], v[152:155], v[210:213], v[14:17]
	v_mfma_f32_16x16x32_bf16 v[10:13], v[160:163], v[210:213], v[10:13]
	v_mfma_f32_16x16x32_bf16 v[6:9], v[168:171], v[210:213], v[6:9]
	v_mfma_f32_16x16x32_bf16 v[2:5], v[176:179], v[210:213], v[2:5]
	s_setprio 0
	s_barrier
	s_add_i32 s51, 0, 0x18000
	v_add_u32_e32 v142, s51, v143
	s_add_i32 s52, 0, 0x1c000
	ds_read_b128 v[148:151], v142
	ds_read_b128 v[152:155], v142 offset:1024
	ds_read_b128 v[156:159], v142 offset:2048
	ds_read_b128 v[160:163], v142 offset:3072
	v_add_u32_e32 v142, s52, v143
	ds_read_b128 v[164:167], v142
	ds_read_b128 v[168:171], v142 offset:1024
	ds_read_b128 v[172:175], v142 offset:2048
	ds_read_b128 v[176:179], v142 offset:3072
	s_add_u32 s24, s24, 0x40000
	s_addc_u32 s25, s25, 0
	s_mov_b32 m0, s36
	v_lshl_add_u64 v[232:233], s[24:25], 0, v[136:137]
	ds_read_b128 v[182:185], v147 offset:32768
	ds_read_b128 v[186:189], v147 offset:33792
	ds_read_b128 v[190:193], v147 offset:34816
	ds_read_b128 v[194:197], v147 offset:35840
	ds_read_b128 v[198:201], v147 offset:36864
	ds_read_b128 v[202:205], v147 offset:37888
	ds_read_b128 v[206:209], v147 offset:38912
	ds_read_b128 v[210:213], v147 offset:39936
	global_load_lds_dwordx4 v[232:233], off
	v_lshl_add_u64 v[232:233], s[24:25], 0, v[132:133]
	s_mov_b32 m0, s37
	s_nop 0
	global_load_lds_dwordx4 v[232:233], off
	s_waitcnt vmcnt(8)
	s_waitcnt lgkmcnt(0)
	s_barrier
	s_setprio 1
	v_mfma_f32_16x16x32_bf16 v[126:129], v[148:151], v[182:185], v[126:129]
	v_mfma_f32_16x16x32_bf16 v[122:125], v[156:159], v[182:185], v[122:125]
	v_mfma_f32_16x16x32_bf16 v[118:121], v[164:167], v[182:185], v[118:121]
	v_mfma_f32_16x16x32_bf16 v[114:117], v[172:175], v[182:185], v[114:117]
	v_mfma_f32_16x16x32_bf16 v[110:113], v[148:151], v[190:193], v[110:113]
	v_mfma_f32_16x16x32_bf16 v[106:109], v[156:159], v[190:193], v[106:109]
	v_mfma_f32_16x16x32_bf16 v[102:105], v[164:167], v[190:193], v[102:105]
	v_mfma_f32_16x16x32_bf16 v[98:101], v[172:175], v[190:193], v[98:101]
	v_mfma_f32_16x16x32_bf16 v[94:97], v[148:151], v[198:201], v[94:97]
	v_mfma_f32_16x16x32_bf16 v[90:93], v[156:159], v[198:201], v[90:93]
	v_mfma_f32_16x16x32_bf16 v[86:89], v[164:167], v[198:201], v[86:89]
	v_mfma_f32_16x16x32_bf16 v[82:85], v[172:175], v[198:201], v[82:85]
	v_mfma_f32_16x16x32_bf16 v[78:81], v[148:151], v[206:209], v[78:81]
	v_mfma_f32_16x16x32_bf16 v[74:77], v[156:159], v[206:209], v[74:77]
	v_mfma_f32_16x16x32_bf16 v[70:73], v[164:167], v[206:209], v[70:73]
	v_mfma_f32_16x16x32_bf16 v[66:69], v[172:175], v[206:209], v[66:69]
	v_mfma_f32_16x16x32_bf16 v[126:129], v[152:155], v[186:189], v[126:129]
	v_mfma_f32_16x16x32_bf16 v[122:125], v[160:163], v[186:189], v[122:125]
	v_mfma_f32_16x16x32_bf16 v[118:121], v[168:171], v[186:189], v[118:121]
	v_mfma_f32_16x16x32_bf16 v[114:117], v[176:179], v[186:189], v[114:117]
	v_mfma_f32_16x16x32_bf16 v[110:113], v[152:155], v[194:197], v[110:113]
	v_mfma_f32_16x16x32_bf16 v[106:109], v[160:163], v[194:197], v[106:109]
	v_mfma_f32_16x16x32_bf16 v[102:105], v[168:171], v[194:197], v[102:105]
	v_mfma_f32_16x16x32_bf16 v[98:101], v[176:179], v[194:197], v[98:101]
	v_mfma_f32_16x16x32_bf16 v[94:97], v[152:155], v[202:205], v[94:97]
	v_mfma_f32_16x16x32_bf16 v[90:93], v[160:163], v[202:205], v[90:93]
	v_mfma_f32_16x16x32_bf16 v[86:89], v[168:171], v[202:205], v[86:89]
	v_mfma_f32_16x16x32_bf16 v[82:85], v[176:179], v[202:205], v[82:85]
	v_mfma_f32_16x16x32_bf16 v[78:81], v[152:155], v[210:213], v[78:81]
	v_mfma_f32_16x16x32_bf16 v[74:77], v[160:163], v[210:213], v[74:77]
	v_mfma_f32_16x16x32_bf16 v[70:73], v[168:171], v[210:213], v[70:73]
	v_mfma_f32_16x16x32_bf16 v[66:69], v[176:179], v[210:213], v[66:69]
	s_setprio 0
	s_barrier
; #define PG8_STAGE(bufoff, gbase, voff) do { _Pragma("unroll") for (int _i = 0; _i < 2; ++_i) \
;         __builtin_amdgcn_global_load_lds((const unsigned*)((const char*)(gbase) + (voff)[_i]), (LAS unsigned*)(lds + (bufoff) + ldsw + _i * 8192), 16, 0, 0); } while (0)
; #define PG8_LDA(dst, b, h) do { _Pragma("unroll") for (int m = 0; m < 4; ++m) _Pragma("unroll") for (int k = 0; k < 2; ++k) dst[m][k] = *(const LAS bf16x8*)(lds + PG8_SA(b, h) + aoff + m * 2048 + k * 1024); } while (0)
; #define PG8_MMA(ai, bj, At, Bt) do { __builtin_amdgcn_s_setprio(1); _Pragma("unroll") for (int m = 0; m < 4; ++m) _Pragma("unroll") for (int n = 0; n < 2; ++n) _Pragma("unroll") for (int k = 0; k < 2; ++k) \
;         acc[ai][bj][m][n] = __builtin_amdgcn_mfma_f32_16x16x32_bf16(Bt[n][k], At[m][k], acc[ai][bj][m][n], 0, 0, 0); __builtin_amdgcn_s_setprio(0); } while (0)
; #define PG8_WAIT_V(n) asm volatile("s_waitcnt vmcnt(" #n ")" ::: "memory")
; #define PG8_WAIT_L(n) asm volatile("s_waitcnt lgkmcnt(" #n ")" ::: "memory")
; #define PG8_BAR __builtin_amdgcn_s_barrier()
; #define PG8_SCHED __builtin_amdgcn_sched_barrier(0)
; template <class Epi>
; __device__ __forceinline__ void gemm_phase(LAS unsigned char* lds, const Gemm g, const StaticOrder& S, const Epi& E) {
;     ...
;             PG8_LDA(At, 1, 1); PG8_STAGE(PG8_SB(1, 0), b3, voffB); PG8_STAGE(PG8_SB(1, 1), b3 + hB, voffB); PG8_STAGE(PG8_SA(1, 0), a3, voffA);
;             PG8_WAIT_V(8); PG8_WAIT_L(0); PG8_BAR; PG8_MMA(1, 0, At, B0); PG8_MMA(1, 1, At, B1); PG8_BAR; PG8_SCHED;
;         }
	s_add_i32 s24, s51, s31
	v_lshl_add_u64 v[214:215], v[214:215], 0, s[88:89]
	s_mov_b32 m0, s24
	ds_read_b128 v[182:185], v147 offset:49152
	ds_read_b128 v[186:189], v147 offset:50176
	ds_read_b128 v[190:193], v147 offset:51200
	ds_read_b128 v[194:197], v147 offset:52224
	ds_read_b128 v[198:201], v147 offset:53248
	ds_read_b128 v[202:205], v147 offset:54272
	ds_read_b128 v[206:209], v147 offset:55296
	ds_read_b128 v[210:213], v147 offset:56320
	global_load_lds_dwordx4 v[214:215], off
	s_add_i32 m0, s24, 0x2000
	s_add_u32 s22, s22, 0x40080
	v_lshl_add_u64 v[214:215], v[216:217], 0, s[88:89]
	s_addc_u32 s23, s23, 0
	s_add_i32 s24, s52, s31
	global_load_lds_dwordx4 v[214:215], off
	v_lshl_add_u64 v[214:215], s[22:23], 0, v[134:135]
	s_mov_b32 m0, s24
	s_nop 0
	global_load_lds_dwordx4 v[214:215], off
	v_lshl_add_u64 v[214:215], s[22:23], 0, v[130:131]
	s_add_i32 m0, s24, 0x2000
	s_nop 0
	global_load_lds_dwordx4 v[214:215], off
	v_lshl_add_u64 v[214:215], v[218:219], 0, s[88:89]
	s_mov_b32 m0, s38
	s_nop 0
	global_load_lds_dwordx4 v[214:215], off
	v_lshl_add_u64 v[214:215], v[220:221], 0, s[88:89]
	s_mov_b32 m0, s39
	s_nop 0
	global_load_lds_dwordx4 v[214:215], off
	s_waitcnt vmcnt(8)
	s_waitcnt lgkmcnt(0)
	s_barrier
	s_setprio 1
	v_mfma_f32_16x16x32_bf16 v[62:65], v[148:151], v[182:185], v[62:65]
	v_mfma_f32_16x16x32_bf16 v[58:61], v[156:159], v[182:185], v[58:61]
	v_mfma_f32_16x16x32_bf16 v[54:57], v[164:167], v[182:185], v[54:57]
	v_mfma_f32_16x16x32_bf16 v[50:53], v[172:175], v[182:185], v[50:53]
	v_mfma_f32_16x16x32_bf16 v[46:49], v[148:151], v[190:193], v[46:49]
	v_mfma_f32_16x16x32_bf16 v[42:45], v[156:159], v[190:193], v[42:45]
	v_mfma_f32_16x16x32_bf16 v[38:41], v[164:167], v[190:193], v[38:41]
	v_mfma_f32_16x16x32_bf16 v[34:37], v[172:175], v[190:193], v[34:37]
	v_mfma_f32_16x16x32_bf16 v[30:33], v[148:151], v[198:201], v[30:33]
	v_mfma_f32_16x16x32_bf16 v[26:29], v[156:159], v[198:201], v[26:29]
	v_mfma_f32_16x16x32_bf16 v[22:25], v[164:167], v[198:201], v[22:25]
	v_mfma_f32_16x16x32_bf16 v[18:21], v[172:175], v[198:201], v[18:21]
	v_mfma_f32_16x16x32_bf16 v[14:17], v[148:151], v[206:209], v[14:17]
	v_mfma_f32_16x16x32_bf16 v[10:13], v[156:159], v[206:209], v[10:13]
	v_mfma_f32_16x16x32_bf16 v[6:9], v[164:167], v[206:209], v[6:9]
	v_mfma_f32_16x16x32_bf16 v[2:5], v[172:175], v[206:209], v[2:5]
	v_mfma_f32_16x16x32_bf16 v[62:65], v[152:155], v[186:189], v[62:65]
	v_mfma_f32_16x16x32_bf16 v[58:61], v[160:163], v[186:189], v[58:61]
	v_mfma_f32_16x16x32_bf16 v[54:57], v[168:171], v[186:189], v[54:57]
	v_mfma_f32_16x16x32_bf16 v[50:53], v[176:179], v[186:189], v[50:53]
	v_mfma_f32_16x16x32_bf16 v[46:49], v[152:155], v[194:197], v[46:49]
	v_mfma_f32_16x16x32_bf16 v[42:45], v[160:163], v[194:197], v[42:45]
	v_mfma_f32_16x16x32_bf16 v[38:41], v[168:171], v[194:197], v[38:41]
	v_mfma_f32_16x16x32_bf16 v[34:37], v[176:179], v[194:197], v[34:37]
	v_mfma_f32_16x16x32_bf16 v[30:33], v[152:155], v[202:205], v[30:33]
	v_mfma_f32_16x16x32_bf16 v[26:29], v[160:163], v[202:205], v[26:29]
	v_mfma_f32_16x16x32_bf16 v[22:25], v[168:171], v[202:205], v[22:25]
	v_mfma_f32_16x16x32_bf16 v[18:21], v[176:179], v[202:205], v[18:21]
	v_mfma_f32_16x16x32_bf16 v[14:17], v[152:155], v[210:213], v[14:17]
	v_mfma_f32_16x16x32_bf16 v[10:13], v[160:163], v[210:213], v[10:13]
	v_mfma_f32_16x16x32_bf16 v[6:9], v[168:171], v[210:213], v[6:9]
	v_mfma_f32_16x16x32_bf16 v[2:5], v[176:179], v[210:213], v[2:5]
	s_setprio 0
	s_barrier
	s_add_i32 s50, s50, 2
	s_add_u32 s20, s20, 0x100
	s_addc_u32 s21, s21, 0
	s_add_u32 s48, s48, 0x100
	s_addc_u32 s49, s49, 0
	s_cmp_gt_u32 s50, 13
	s_cbranch_scc0 .LBB0_1550
	s_and_b64 vcc, exec, s[10:11]
	s_cbranch_vccz .LBB0_1553
	s_barrier

; #define PG8_STAGE(bufoff, gbase, voff) do { _Pragma("unroll") for (int _i = 0; _i < 2; ++_i) \
;         __builtin_amdgcn_global_load_lds((const unsigned*)((const char*)(gbase) + (voff)[_i]), (LAS unsigned*)(lds + (bufoff) + ldsw + _i * 8192), 16, 0, 0); } while (0)
; #define PG8_LDA(dst, b, h) do { _Pragma("unroll") for (int m = 0; m < 4; ++m) _Pragma("unroll") for (int k = 0; k < 2; ++k) dst[m][k] = *(const LAS bf16x8*)(lds + PG8_SA(b, h) + aoff + m * 2048 + k * 1024); } while (0)
; #define PG8_LDB(dst, b, h) do { _Pragma("unroll") for (int n = 0; n < 2; ++n) _Pragma("unroll") for (int k = 0; k < 2; ++k) dst[n][k] = *(const LAS bf16x8*)(lds + PG8_SB(b, h) + boff + n * 2048 + k * 1024); } while (0)
; #define PG8_MMA(ai, bj, At, Bt) do { __builtin_amdgcn_s_setprio(1); _Pragma("unroll") for (int m = 0; m < 4; ++m) _Pragma("unroll") for (int n = 0; n < 2; ++n) _Pragma("unroll") for (int k = 0; k < 2; ++k) \
;         acc[ai][bj][m][n] = __builtin_amdgcn_mfma_f32_16x16x32_bf16(Bt[n][k], At[m][k], acc[ai][bj][m][n], 0, 0, 0); __builtin_amdgcn_s_setprio(0); } while (0)
; #define PG8_WAIT_V(n) asm volatile("s_waitcnt vmcnt(" #n ")" ::: "memory")
; #define PG8_WAIT_L(n) asm volatile("s_waitcnt lgkmcnt(" #n ")" ::: "memory")
; #define PG8_BAR __builtin_amdgcn_s_barrier()
; #define PG8_SCHED __builtin_amdgcn_sched_barrier(0)
; template <class Epi>
; __device__ __forceinline__ void gemm_phase(LAS unsigned char* lds, const Gemm g, const StaticOrder& S, const Epi& E) {
;     ...
;         for (int t = 0; t < nt; t += 2) {
;             const bool last = (t == nt - 2);
;             const char* a1 = cA + (size_t)(t + 1) * kstep;
;             const char* a2 = last ? nA : cA + (size_t)(t + 2) * kstep; const char* b2 = last ? nB : cB + (size_t)(t + 2) * kstep;
;             const char* a3 = a2 + kstep; const char* b3 = b2 + kstep;
;             PG8_LDB(B0, 0, 0); PG8_LDB(B1, 0, 1); PG8_SCHED; PG8_LDA(At, 0, 0); PG8_STAGE(PG8_SA(1, 1), a1 + hA, voffA);
;             PG8_WAIT_V(8); PG8_WAIT_L(0); PG8_BAR; PG8_MMA(0, 0, At, B0); PG8_MMA(0, 1, At, B1); PG8_BAR; PG8_SCHED;
;             PG8_LDA(At, 0, 1); PG8_STAGE(PG8_SB(0, 0), b2, voffB); PG8_STAGE(PG8_SB(0, 1), b2 + hB, voffB); PG8_STAGE(PG8_SA(0, 0), a2, voffA);
;             PG8_WAIT_V(8); PG8_WAIT_L(0); PG8_BAR; PG8_MMA(1, 0, At, B0); PG8_MMA(1, 1, At, B1); PG8_BAR; PG8_SCHED;
.LBB0_1632:
	s_add_u32 s8, s10, 0x100
	s_addc_u32 s9, s11, 0
	s_add_i32 s70, 0, 0x10000
	s_cmp_eq_u32 s67, 40
	s_cselect_b32 s45, s39, s9
	s_cselect_b32 s44, s38, s8
	s_cselect_b32 s43, s41, s37
	s_cselect_b32 s42, s40, s35
	s_add_i32 s71, 0, 0x14000
	s_waitcnt lgkmcnt(0)
	v_add_u32_e32 v158, s70, v180
	v_add_u32_e32 v174, s71, v180
	ds_read_b128 v[146:149], v158
	ds_read_b128 v[150:153], v158 offset:1024
	ds_read_b128 v[154:157], v158 offset:2048
	ds_read_b128 v[158:161], v158 offset:3072
	ds_read_b128 v[162:165], v174
	ds_read_b128 v[166:169], v174 offset:1024
	ds_read_b128 v[170:173], v174 offset:2048
	ds_read_b128 v[174:177], v174 offset:3072
	v_lshl_add_u64 v[178:179], s[10:11], 0, v[142:143]
	s_add_i32 m0, s52, 0xc000
	ds_read_b128 v[182:185], v192
	ds_read_b128 v[196:199], v192 offset:1024
	ds_read_b128 v[200:203], v192 offset:2048
	ds_read_b128 v[204:207], v192 offset:3072
	ds_read_b128 v[208:211], v192 offset:4096
	ds_read_b128 v[212:215], v192 offset:5120
	ds_read_b128 v[216:219], v192 offset:6144
	ds_read_b128 v[232:235], v192 offset:7168
	global_load_lds_dwordx4 v[178:179], off
	v_lshl_add_u64 v[178:179], s[10:11], 0, v[144:145]
	s_add_i32 m0, s52, 0xe000
	s_nop 0
	global_load_lds_dwordx4 v[178:179], off
	s_waitcnt vmcnt(8)
	s_waitcnt lgkmcnt(0)
	s_barrier
	s_setprio 1
	v_mfma_f32_16x16x32_bf16 v[26:29], v[146:149], v[182:185], v[26:29]
	v_mfma_f32_16x16x32_bf16 v[30:33], v[154:157], v[182:185], v[30:33]
	v_mfma_f32_16x16x32_bf16 v[42:45], v[162:165], v[182:185], v[42:45]
	v_mfma_f32_16x16x32_bf16 v[46:49], v[170:173], v[182:185], v[46:49]
	v_mfma_f32_16x16x32_bf16 v[58:61], v[146:149], v[200:203], v[58:61]
	v_mfma_f32_16x16x32_bf16 v[62:65], v[154:157], v[200:203], v[62:65]
	v_mfma_f32_16x16x32_bf16 v[74:77], v[162:165], v[200:203], v[74:77]
	v_mfma_f32_16x16x32_bf16 v[78:81], v[170:173], v[200:203], v[78:81]
	v_mfma_f32_16x16x32_bf16 v[90:93], v[146:149], v[208:211], v[90:93]
	v_mfma_f32_16x16x32_bf16 v[94:97], v[154:157], v[208:211], v[94:97]
	v_mfma_f32_16x16x32_bf16 v[106:109], v[162:165], v[208:211], v[106:109]
	v_mfma_f32_16x16x32_bf16 v[110:113], v[170:173], v[208:211], v[110:113]
	v_mfma_f32_16x16x32_bf16 v[114:117], v[146:149], v[216:219], v[114:117]
	v_mfma_f32_16x16x32_bf16 v[118:121], v[154:157], v[216:219], v[118:121]
	v_mfma_f32_16x16x32_bf16 v[126:129], v[162:165], v[216:219], v[126:129]
	v_mfma_f32_16x16x32_bf16 v[122:125], v[170:173], v[216:219], v[122:125]
	v_mfma_f32_16x16x32_bf16 v[26:29], v[150:153], v[196:199], v[26:29]
	v_mfma_f32_16x16x32_bf16 v[30:33], v[158:161], v[196:199], v[30:33]
	v_mfma_f32_16x16x32_bf16 v[42:45], v[166:169], v[196:199], v[42:45]
	v_mfma_f32_16x16x32_bf16 v[46:49], v[174:177], v[196:199], v[46:49]
	v_mfma_f32_16x16x32_bf16 v[58:61], v[150:153], v[204:207], v[58:61]
	v_mfma_f32_16x16x32_bf16 v[62:65], v[158:161], v[204:207], v[62:65]
	v_mfma_f32_16x16x32_bf16 v[74:77], v[166:169], v[204:207], v[74:77]
	v_mfma_f32_16x16x32_bf16 v[78:81], v[174:177], v[204:207], v[78:81]
	v_mfma_f32_16x16x32_bf16 v[90:93], v[150:153], v[212:215], v[90:93]
	v_mfma_f32_16x16x32_bf16 v[94:97], v[158:161], v[212:215], v[94:97]
	v_mfma_f32_16x16x32_bf16 v[106:109], v[166:169], v[212:215], v[106:109]
	v_mfma_f32_16x16x32_bf16 v[110:113], v[174:177], v[212:215], v[110:113]
	v_mfma_f32_16x16x32_bf16 v[114:117], v[150:153], v[232:235], v[114:117]
	v_mfma_f32_16x16x32_bf16 v[118:121], v[158:161], v[232:235], v[118:121]
	v_mfma_f32_16x16x32_bf16 v[126:129], v[166:169], v[232:235], v[126:129]
	v_mfma_f32_16x16x32_bf16 v[122:125], v[174:177], v[232:235], v[122:125]
	s_setprio 0
	s_barrier
	s_add_i32 s10, s70, s47
	v_lshl_add_u64 v[178:179], s[42:43], 0, v[132:133]
	s_mov_b32 m0, s10
	ds_read_b128 v[182:185], v192 offset:16384
	ds_read_b128 v[196:199], v192 offset:17408
	ds_read_b128 v[200:203], v192 offset:18432
	ds_read_b128 v[204:207], v192 offset:19456
	ds_read_b128 v[208:211], v192 offset:20480
	ds_read_b128 v[212:215], v192 offset:21504
	ds_read_b128 v[216:219], v192 offset:22528
	ds_read_b128 v[232:235], v192 offset:23552
	global_load_lds_dwordx4 v[178:179], off
	s_add_i32 m0, s10, 0x2000
	s_add_u32 s10, s42, 0xb0000
	v_lshl_add_u64 v[186:187], s[42:43], 0, v[136:137]
	s_addc_u32 s11, s43, 0
	s_add_i32 s70, s71, s47
	global_load_lds_dwordx4 v[186:187], off
	v_lshl_add_u64 v[220:221], s[10:11], 0, v[132:133]
	s_mov_b32 m0, s70
	v_lshl_add_u64 v[236:237], s[44:45], 0, v[134:135]
	global_load_lds_dwordx4 v[220:221], off
	v_lshl_add_u64 v[220:221], s[10:11], 0, v[136:137]
	s_add_i32 m0, s70, 0x2000
	s_nop 0
	global_load_lds_dwordx4 v[220:221], off
	v_lshl_add_u64 v[220:221], s[44:45], 0, v[130:131]
	s_mov_b32 m0, s52
	s_nop 0
	global_load_lds_dwordx4 v[220:221], off
	s_mov_b32 m0, s53
	s_nop 0
	global_load_lds_dwordx4 v[236:237], off
	s_waitcnt vmcnt(8)
	s_waitcnt lgkmcnt(0)
	s_barrier
; #define PG8_STAGE(bufoff, gbase, voff) do { _Pragma("unroll") for (int _i = 0; _i < 2; ++_i) \
;         __builtin_amdgcn_global_load_lds((const unsigned*)((const char*)(gbase) + (voff)[_i]), (LAS unsigned*)(lds + (bufoff) + ldsw + _i * 8192), 16, 0, 0); } while (0)
; #define PG8_LDA(dst, b, h) do { _Pragma("unroll") for (int m = 0; m < 4; ++m) _Pragma("unroll") for (int k = 0; k < 2; ++k) dst[m][k] = *(const LAS bf16x8*)(lds + PG8_SA(b, h) + aoff + m * 2048 + k * 1024); } while (0)
; #define PG8_LDB(dst, b, h) do { _Pragma("unroll") for (int n = 0; n < 2; ++n) _Pragma("unroll") for (int k = 0; k < 2; ++k) dst[n][k] = *(const LAS bf16x8*)(lds + PG8_SB(b, h) + boff + n * 2048 + k * 1024); } while (0)
; #define PG8_MMA(ai, bj, At, Bt) do { __builtin_amdgcn_s_setprio(1); _Pragma("unroll") for (int m = 0; m < 4; ++m) _Pragma("unroll") for (int n = 0; n < 2; ++n) _Pragma("unroll") for (int k = 0; k < 2; ++k) \
;         acc[ai][bj][m][n] = __builtin_amdgcn_mfma_f32_16x16x32_bf16(Bt[n][k], At[m][k], acc[ai][bj][m][n], 0, 0, 0); __builtin_amdgcn_s_setprio(0); } while (0)
; #define PG8_WAIT_V(n) asm volatile("s_waitcnt vmcnt(" #n ")" ::: "memory")
; #define PG8_WAIT_L(n) asm volatile("s_waitcnt lgkmcnt(" #n ")" ::: "memory")
; #define PG8_BAR __builtin_amdgcn_s_barrier()
; #define PG8_SCHED __builtin_amdgcn_sched_barrier(0)
; template <class Epi>
; __device__ __forceinline__ void gemm_phase(LAS unsigned char* lds, const Gemm g, const StaticOrder& S, const Epi& E) {
;     ...
;             PG8_WAIT_V(8); PG8_WAIT_L(0); PG8_BAR; PG8_MMA(1, 0, At, B0); PG8_MMA(1, 1, At, B1); PG8_BAR; PG8_SCHED;
;             PG8_LDB(B0, 1, 0); PG8_LDB(B1, 1, 1); PG8_SCHED; PG8_LDA(At, 1, 0); PG8_STAGE(PG8_SA(0, 1), a2 + hA, voffA);
;             PG8_WAIT_V(8); PG8_WAIT_L(0); PG8_BAR; PG8_MMA(0, 0, At, B0); PG8_MMA(0, 1, At, B1); PG8_BAR; PG8_SCHED;
	s_setprio 1
	v_mfma_f32_16x16x32_bf16 v[102:105], v[146:149], v[182:185], v[102:105]
	v_mfma_f32_16x16x32_bf16 v[98:101], v[154:157], v[182:185], v[98:101]
	v_mfma_f32_16x16x32_bf16 v[86:89], v[162:165], v[182:185], v[86:89]
	v_mfma_f32_16x16x32_bf16 v[82:85], v[170:173], v[182:185], v[82:85]
	v_mfma_f32_16x16x32_bf16 v[70:73], v[146:149], v[200:203], v[70:73]
	v_mfma_f32_16x16x32_bf16 v[66:69], v[154:157], v[200:203], v[66:69]
	v_mfma_f32_16x16x32_bf16 v[54:57], v[162:165], v[200:203], v[54:57]
	v_mfma_f32_16x16x32_bf16 v[50:53], v[170:173], v[200:203], v[50:53]
	v_mfma_f32_16x16x32_bf16 v[38:41], v[146:149], v[208:211], v[38:41]
	v_mfma_f32_16x16x32_bf16 v[34:37], v[154:157], v[208:211], v[34:37]
	v_mfma_f32_16x16x32_bf16 v[22:25], v[162:165], v[208:211], v[22:25]
	v_mfma_f32_16x16x32_bf16 v[18:21], v[170:173], v[208:211], v[18:21]
	v_mfma_f32_16x16x32_bf16 v[14:17], v[146:149], v[216:219], v[14:17]
	v_mfma_f32_16x16x32_bf16 v[10:13], v[154:157], v[216:219], v[10:13]
	v_mfma_f32_16x16x32_bf16 v[6:9], v[162:165], v[216:219], v[6:9]
	v_mfma_f32_16x16x32_bf16 v[2:5], v[170:173], v[216:219], v[2:5]
	v_mfma_f32_16x16x32_bf16 v[102:105], v[150:153], v[196:199], v[102:105]
	v_mfma_f32_16x16x32_bf16 v[98:101], v[158:161], v[196:199], v[98:101]
	v_mfma_f32_16x16x32_bf16 v[86:89], v[166:169], v[196:199], v[86:89]
	v_mfma_f32_16x16x32_bf16 v[82:85], v[174:177], v[196:199], v[82:85]
	v_mfma_f32_16x16x32_bf16 v[70:73], v[150:153], v[204:207], v[70:73]
	v_mfma_f32_16x16x32_bf16 v[66:69], v[158:161], v[204:207], v[66:69]
	v_mfma_f32_16x16x32_bf16 v[54:57], v[166:169], v[204:207], v[54:57]
	v_mfma_f32_16x16x32_bf16 v[50:53], v[174:177], v[204:207], v[50:53]
	v_mfma_f32_16x16x32_bf16 v[38:41], v[150:153], v[212:215], v[38:41]
	v_mfma_f32_16x16x32_bf16 v[34:37], v[158:161], v[212:215], v[34:37]
	v_mfma_f32_16x16x32_bf16 v[22:25], v[166:169], v[212:215], v[22:25]
	v_mfma_f32_16x16x32_bf16 v[18:21], v[174:177], v[212:215], v[18:21]
	v_mfma_f32_16x16x32_bf16 v[14:17], v[150:153], v[232:235], v[14:17]
	v_mfma_f32_16x16x32_bf16 v[10:13], v[158:161], v[232:235], v[10:13]
	v_mfma_f32_16x16x32_bf16 v[6:9], v[166:169], v[232:235], v[6:9]
	v_mfma_f32_16x16x32_bf16 v[2:5], v[174:177], v[232:235], v[2:5]
	s_setprio 0
	s_barrier
	s_add_i32 s70, 0, 0x18000
	s_add_i32 s71, 0, 0x1c000
	v_add_u32_e32 v158, s70, v180
	v_add_u32_e32 v174, s71, v180
	ds_read_b128 v[146:149], v158
	ds_read_b128 v[150:153], v158 offset:1024
	ds_read_b128 v[154:157], v158 offset:2048
	ds_read_b128 v[158:161], v158 offset:3072
	ds_read_b128 v[162:165], v174
	ds_read_b128 v[166:169], v174 offset:1024
	ds_read_b128 v[170:173], v174 offset:2048
	ds_read_b128 v[174:177], v174 offset:3072
	s_add_u32 s10, s44, 0xb0000
	s_addc_u32 s11, s45, 0
	s_mov_b32 m0, s54
	v_lshl_add_u64 v[238:239], s[10:11], 0, v[130:131]
	ds_read_b128 v[182:185], v192 offset:32768
	ds_read_b128 v[196:199], v192 offset:33792
	ds_read_b128 v[200:203], v192 offset:34816
	ds_read_b128 v[204:207], v192 offset:35840
	ds_read_b128 v[208:211], v192 offset:36864
	ds_read_b128 v[212:215], v192 offset:37888
	ds_read_b128 v[216:219], v192 offset:38912
	ds_read_b128 v[232:235], v192 offset:39936
	global_load_lds_dwordx4 v[238:239], off
	v_lshl_add_u64 v[238:239], s[10:11], 0, v[134:135]
	s_mov_b32 m0, s55
	s_nop 0
	global_load_lds_dwordx4 v[238:239], off
	s_waitcnt vmcnt(8)
	s_waitcnt lgkmcnt(0)
	s_barrier
	s_setprio 1
	v_mfma_f32_16x16x32_bf16 v[26:29], v[146:149], v[182:185], v[26:29]
	v_mfma_f32_16x16x32_bf16 v[30:33], v[154:157], v[182:185], v[30:33]
	v_mfma_f32_16x16x32_bf16 v[42:45], v[162:165], v[182:185], v[42:45]
	v_mfma_f32_16x16x32_bf16 v[46:49], v[170:173], v[182:185], v[46:49]
	v_mfma_f32_16x16x32_bf16 v[58:61], v[146:149], v[200:203], v[58:61]
	v_mfma_f32_16x16x32_bf16 v[62:65], v[154:157], v[200:203], v[62:65]
	v_mfma_f32_16x16x32_bf16 v[74:77], v[162:165], v[200:203], v[74:77]
	v_mfma_f32_16x16x32_bf16 v[78:81], v[170:173], v[200:203], v[78:81]
	v_mfma_f32_16x16x32_bf16 v[90:93], v[146:149], v[208:211], v[90:93]
	v_mfma_f32_16x16x32_bf16 v[94:97], v[154:157], v[208:211], v[94:97]
	v_mfma_f32_16x16x32_bf16 v[106:109], v[162:165], v[208:211], v[106:109]
	v_mfma_f32_16x16x32_bf16 v[110:113], v[170:173], v[208:211], v[110:113]
	v_mfma_f32_16x16x32_bf16 v[114:117], v[146:149], v[216:219], v[114:117]
	v_mfma_f32_16x16x32_bf16 v[118:121], v[154:157], v[216:219], v[118:121]
	v_mfma_f32_16x16x32_bf16 v[126:129], v[162:165], v[216:219], v[126:129]
	v_mfma_f32_16x16x32_bf16 v[122:125], v[170:173], v[216:219], v[122:125]
	v_mfma_f32_16x16x32_bf16 v[26:29], v[150:153], v[196:199], v[26:29]
	v_mfma_f32_16x16x32_bf16 v[30:33], v[158:161], v[196:199], v[30:33]
	v_mfma_f32_16x16x32_bf16 v[42:45], v[166:169], v[196:199], v[42:45]
	v_mfma_f32_16x16x32_bf16 v[46:49], v[174:177], v[196:199], v[46:49]
	v_mfma_f32_16x16x32_bf16 v[58:61], v[150:153], v[204:207], v[58:61]
	v_mfma_f32_16x16x32_bf16 v[62:65], v[158:161], v[204:207], v[62:65]
	v_mfma_f32_16x16x32_bf16 v[74:77], v[166:169], v[204:207], v[74:77]
	v_mfma_f32_16x16x32_bf16 v[78:81], v[174:177], v[204:207], v[78:81]
	v_mfma_f32_16x16x32_bf16 v[90:93], v[150:153], v[212:215], v[90:93]
	v_mfma_f32_16x16x32_bf16 v[94:97], v[158:161], v[212:215], v[94:97]
	v_mfma_f32_16x16x32_bf16 v[106:109], v[166:169], v[212:215], v[106:109]
	v_mfma_f32_16x16x32_bf16 v[110:113], v[174:177], v[212:215], v[110:113]
	v_mfma_f32_16x16x32_bf16 v[114:117], v[150:153], v[232:235], v[114:117]
	v_mfma_f32_16x16x32_bf16 v[118:121], v[158:161], v[232:235], v[118:121]
	v_mfma_f32_16x16x32_bf16 v[126:129], v[166:169], v[232:235], v[126:129]
	v_mfma_f32_16x16x32_bf16 v[122:125], v[174:177], v[232:235], v[122:125]
	s_setprio 0
	s_barrier
; #define PG8_STAGE(bufoff, gbase, voff) do { _Pragma("unroll") for (int _i = 0; _i < 2; ++_i) \
;         __builtin_amdgcn_global_load_lds((const unsigned*)((const char*)(gbase) + (voff)[_i]), (LAS unsigned*)(lds + (bufoff) + ldsw + _i * 8192), 16, 0, 0); } while (0)
; #define PG8_LDA(dst, b, h) do { _Pragma("unroll") for (int m = 0; m < 4; ++m) _Pragma("unroll") for (int k = 0; k < 2; ++k) dst[m][k] = *(const LAS bf16x8*)(lds + PG8_SA(b, h) + aoff + m * 2048 + k * 1024); } while (0)
; #define PG8_MMA(ai, bj, At, Bt) do { __builtin_amdgcn_s_setprio(1); _Pragma("unroll") for (int m = 0; m < 4; ++m) _Pragma("unroll") for (int n = 0; n < 2; ++n) _Pragma("unroll") for (int k = 0; k < 2; ++k) \
;         acc[ai][bj][m][n] = __builtin_amdgcn_mfma_f32_16x16x32_bf16(Bt[n][k], At[m][k], acc[ai][bj][m][n], 0, 0, 0); __builtin_amdgcn_s_setprio(0); } while (0)
; #define PG8_WAIT_V(n) asm volatile("s_waitcnt vmcnt(" #n ")" ::: "memory")
; #define PG8_WAIT_L(n) asm volatile("s_waitcnt lgkmcnt(" #n ")" ::: "memory")
; #define PG8_BAR __builtin_amdgcn_s_barrier()
; #define PG8_SCHED __builtin_amdgcn_sched_barrier(0)
; template <class Epi>
; __device__ __forceinline__ void gemm_phase(LAS unsigned char* lds, const Gemm g, const StaticOrder& S, const Epi& E) {
;     ...
;             PG8_LDA(At, 1, 1); PG8_STAGE(PG8_SB(1, 0), b3, voffB); PG8_STAGE(PG8_SB(1, 1), b3 + hB, voffB); PG8_STAGE(PG8_SA(1, 0), a3, voffA);
;             PG8_WAIT_V(8); PG8_WAIT_L(0); PG8_BAR; PG8_MMA(1, 0, At, B0); PG8_MMA(1, 1, At, B1); PG8_BAR; PG8_SCHED;
;         }
	s_add_i32 s10, s70, s47
	v_lshl_add_u64 v[178:179], v[178:179], 0, s[88:89]
	s_mov_b32 m0, s10
	ds_read_b128 v[182:185], v192 offset:49152
	ds_read_b128 v[196:199], v192 offset:50176
	ds_read_b128 v[200:203], v192 offset:51200
	ds_read_b128 v[204:207], v192 offset:52224
	ds_read_b128 v[208:211], v192 offset:53248
	ds_read_b128 v[212:215], v192 offset:54272
	ds_read_b128 v[216:219], v192 offset:55296
	ds_read_b128 v[232:235], v192 offset:56320
	global_load_lds_dwordx4 v[178:179], off
	s_add_i32 m0, s10, 0x2000
	s_add_u32 s10, s42, 0xb0080
	v_lshl_add_u64 v[178:179], v[186:187], 0, s[88:89]
	s_addc_u32 s11, s43, 0
	s_add_i32 s42, s71, s47
	global_load_lds_dwordx4 v[178:179], off
	v_lshl_add_u64 v[178:179], s[10:11], 0, v[132:133]
	s_mov_b32 m0, s42
	s_nop 0
	global_load_lds_dwordx4 v[178:179], off
	v_lshl_add_u64 v[178:179], s[10:11], 0, v[136:137]
	s_add_i32 m0, s42, 0x2000
	s_nop 0
	global_load_lds_dwordx4 v[178:179], off
	v_lshl_add_u64 v[178:179], v[220:221], 0, s[88:89]
	s_mov_b32 m0, s56
	s_nop 0
	global_load_lds_dwordx4 v[178:179], off
	v_lshl_add_u64 v[178:179], v[236:237], 0, s[88:89]
	s_mov_b32 m0, s57
	s_nop 0
	global_load_lds_dwordx4 v[178:179], off
	s_waitcnt vmcnt(8)
	s_waitcnt lgkmcnt(0)
	s_barrier
	s_setprio 1
	v_mfma_f32_16x16x32_bf16 v[102:105], v[146:149], v[182:185], v[102:105]
	v_mfma_f32_16x16x32_bf16 v[98:101], v[154:157], v[182:185], v[98:101]
	v_mfma_f32_16x16x32_bf16 v[86:89], v[162:165], v[182:185], v[86:89]
	v_mfma_f32_16x16x32_bf16 v[82:85], v[170:173], v[182:185], v[82:85]
	v_mfma_f32_16x16x32_bf16 v[70:73], v[146:149], v[200:203], v[70:73]
	v_mfma_f32_16x16x32_bf16 v[66:69], v[154:157], v[200:203], v[66:69]
	v_mfma_f32_16x16x32_bf16 v[54:57], v[162:165], v[200:203], v[54:57]
	v_mfma_f32_16x16x32_bf16 v[50:53], v[170:173], v[200:203], v[50:53]
	v_mfma_f32_16x16x32_bf16 v[38:41], v[146:149], v[208:211], v[38:41]
	v_mfma_f32_16x16x32_bf16 v[34:37], v[154:157], v[208:211], v[34:37]
	v_mfma_f32_16x16x32_bf16 v[22:25], v[162:165], v[208:211], v[22:25]
	v_mfma_f32_16x16x32_bf16 v[18:21], v[170:173], v[208:211], v[18:21]
	v_mfma_f32_16x16x32_bf16 v[14:17], v[146:149], v[216:219], v[14:17]
	v_mfma_f32_16x16x32_bf16 v[10:13], v[154:157], v[216:219], v[10:13]
	v_mfma_f32_16x16x32_bf16 v[6:9], v[162:165], v[216:219], v[6:9]
	v_mfma_f32_16x16x32_bf16 v[2:5], v[170:173], v[216:219], v[2:5]
	v_mfma_f32_16x16x32_bf16 v[102:105], v[150:153], v[196:199], v[102:105]
	v_mfma_f32_16x16x32_bf16 v[98:101], v[158:161], v[196:199], v[98:101]
	v_mfma_f32_16x16x32_bf16 v[86:89], v[166:169], v[196:199], v[86:89]
	v_mfma_f32_16x16x32_bf16 v[82:85], v[174:177], v[196:199], v[82:85]
	v_mfma_f32_16x16x32_bf16 v[70:73], v[150:153], v[204:207], v[70:73]
	v_mfma_f32_16x16x32_bf16 v[66:69], v[158:161], v[204:207], v[66:69]
	v_mfma_f32_16x16x32_bf16 v[54:57], v[166:169], v[204:207], v[54:57]
	v_mfma_f32_16x16x32_bf16 v[50:53], v[174:177], v[204:207], v[50:53]
	v_mfma_f32_16x16x32_bf16 v[38:41], v[150:153], v[212:215], v[38:41]
	v_mfma_f32_16x16x32_bf16 v[34:37], v[158:161], v[212:215], v[34:37]
	v_mfma_f32_16x16x32_bf16 v[22:25], v[166:169], v[212:215], v[22:25]
	v_mfma_f32_16x16x32_bf16 v[18:21], v[174:177], v[212:215], v[18:21]
	v_mfma_f32_16x16x32_bf16 v[14:17], v[150:153], v[232:235], v[14:17]
	v_mfma_f32_16x16x32_bf16 v[10:13], v[158:161], v[232:235], v[10:13]
	v_mfma_f32_16x16x32_bf16 v[6:9], v[166:169], v[232:235], v[6:9]
	v_mfma_f32_16x16x32_bf16 v[2:5], v[174:177], v[232:235], v[2:5]
	s_setprio 0
	s_barrier
	s_add_i32 s67, s67, 2
	s_add_u32 s35, s35, 0x100
	s_addc_u32 s37, s37, 0
	s_cmp_gt_u32 s67, 41
	s_mov_b64 s[10:11], s[8:9]
	s_cbranch_scc0 .LBB0_1632
	s_and_b64 vcc, exec, s[20:21]
	s_cbranch_vccz .LBB0_1635
	s_barrier
